# FFN gate/up epilogue: second row-half ssq loads issued with the first half's (no wait on the first half's stores), on top of v5
# speedup vs baseline: 1.0098x; 1.0057x over previous
; __device__ __forceinline__ unsigned pk2(float lo, float hi) { f32x2_t v = {lo, hi}; bf16x2_t b = __builtin_convertvector(v, bf16x2_t); return __builtin_bit_cast(unsigned, b); }
; __device__ __forceinline__ float sigm(float x) { return frcp(1.f + fexp2(-LOG2E * x)); }
;   __device__ __forceinline__ void operator()(const pg8::f32x4 (&acc)[2][2][4][2], const pg8::Unit& u, int wr, int wc, int fr, int fq) const {
;     int z; asm volatile("v_mov_b32 %0, 0" : "=v"(z));
;     const int row0 = u.pm * 256 + wr * 64 + fr + z, col0 = u.pn * 128 + wc * 32 + 8 * fq + z;
; #pragma unroll
;     for (int ai = 0; ai < 2; ++ai) {
;       float rs[4];
; #pragma unroll
;       for (int m = 0; m < 4; ++m) { const f32x4 a = *(const f32x4*)(ssq + (unsigned)(row0 + ai * 128 + m * 16) * 16 + 4 * fq); rs[m] = (a[0] + a[1]) + (a[2] + a[3]); }
; #pragma unroll
;       for (int m = 0; m < 4; ++m) { float v = rs[m]; v += __shfl_xor(v, 16); v += __shfl_xor(v, 32); rs[m] = rsqrtf(v * (1.f / 1024.f) + EPS); }
; #pragma unroll
;       for (int m = 0; m < 4; ++m) {
;         const float r = rs[m]; float v[8];
; #pragma unroll
;         for (int n = 0; n < 2; ++n)
; #pragma unroll
;           for (int c = 0; c < 4; ++c) { const float g = acc[ai][0][m][n][c] * r, uu = acc[ai][1][m][n][c] * r; v[4 * n + c] = g * sigm(g) * uu; }
;         u32x4 w; w.x = pk2(v[0], v[1]); w.y = pk2(v[2], v[3]); w.z = pk2(v[4], v[5]); w.w = pk2(v[6], v[7]);
.LBB0_184:
	s_lshl_b32 s4, s4, 8
	v_mov_b32 v150, 0
	v_xor_b32_e32 v173, 32, v171
	v_add3_u32 v190, s4, v151, v150
	v_lshlrev_b32_e32 v136, 4, v190
	v_lshl_add_u64 v[148:149], v[136:137], 2, v[138:139]
	global_load_dwordx4 v[174:177], v[148:149], off
	v_add_u32_e32 v148, 0x100, v136
	v_mov_b32_e32 v149, v137
	v_lshl_add_u64 v[148:149], v[148:149], 2, v[138:139]
	global_load_dwordx4 v[178:181], v[148:149], off
	v_add_u32_e32 v148, 0x200, v136
	v_mov_b32_e32 v149, v137
	v_lshl_add_u64 v[148:149], v[148:149], 2, v[138:139]
	global_load_dwordx4 v[182:185], v[148:149], off
	v_add_u32_e32 v148, 0x300, v136
	v_mov_b32_e32 v149, v137
	v_lshl_add_u64 v[148:149], v[148:149], 2, v[138:139]
	global_load_dwordx4 v[186:189], v[148:149], off
	v_add_u32_e32 v216, 0x800, v136
	v_mov_b32_e32 v217, v137
	v_lshl_add_u64 v[216:217], v[216:217], 2, v[138:139]
	global_load_dwordx4 v[200:203], v[216:217], off
	v_add_u32_e32 v216, 0x900, v136
	v_mov_b32_e32 v217, v137
	v_lshl_add_u64 v[216:217], v[216:217], 2, v[138:139]
	global_load_dwordx4 v[204:207], v[216:217], off
	v_add_u32_e32 v216, 0xa00, v136
	v_mov_b32_e32 v217, v137
	v_lshl_add_u64 v[216:217], v[216:217], 2, v[138:139]
	global_load_dwordx4 v[208:211], v[216:217], off
	v_add_u32_e32 v216, 0xb00, v136
	v_mov_b32_e32 v217, v137
	v_lshl_add_u64 v[216:217], v[216:217], 2, v[138:139]
	global_load_dwordx4 v[212:215], v[216:217], off
	v_and_b32_e32 v149, 64, v171
	v_xor_b32_e32 v148, 16, v171
	v_add_u32_e32 v191, 64, v149
	v_cmp_lt_i32_e32 vcc, v148, v191
	v_lshl_or_b32 v152, s5, 7, v154
	s_waitcnt vmcnt(0)
	v_mov_b32_e32 v149, v176
	v_cndmask_b32_e32 v148, v171, v148, vcc
	v_lshlrev_b32_e32 v172, 2, v148
	v_mov_b32_e32 v148, v175
	v_mov_b32_e32 v175, v177
	v_pk_add_f32 v[148:149], v[148:149], v[174:175]
	v_mov_b32_e32 v174, v179
	v_mov_b32_e32 v175, v180
	v_mov_b32_e32 v179, v181
	v_mov_b32_e32 v176, v183
	v_mov_b32_e32 v177, v184
	v_mov_b32_e32 v183, v185
	v_mov_b32_e32 v180, v187
	v_mov_b32_e32 v181, v188
	v_mov_b32_e32 v187, v189
	v_pk_add_f32 v[174:175], v[174:175], v[178:179]
	v_pk_add_f32 v[176:177], v[176:177], v[182:183]
	v_pk_add_f32 v[178:179], v[180:181], v[186:187]
	v_mov_b32_e32 v181, v148
	v_mov_b32_e32 v180, v174
	v_mov_b32_e32 v148, v175
	v_mov_b32_e32 v174, v178
	v_mov_b32_e32 v175, v176
	v_mov_b32_e32 v176, v179
	v_pk_add_f32 v[148:149], v[180:181], v[148:149]
	v_pk_add_f32 v[174:175], v[174:175], v[176:177]
	ds_bpermute_b32 v177, v172, v149
	ds_bpermute_b32 v176, v172, v148
	ds_bpermute_b32 v179, v172, v175
	ds_bpermute_b32 v178, v172, v174
	v_cmp_lt_i32_e32 vcc, v173, v191
	v_add_u32_e32 v182, v152, v150
	s_waitcnt lgkmcnt(2)
	v_pk_add_f32 v[176:177], v[148:149], v[176:177]
	v_cndmask_b32_e32 v173, v171, v173, vcc
	v_lshlrev_b32_e32 v173, 2, v173
	s_waitcnt lgkmcnt(0)
	v_pk_add_f32 v[174:175], v[174:175], v[178:179]
	ds_bpermute_b32 v179, v173, v177
	ds_bpermute_b32 v178, v173, v176
	ds_bpermute_b32 v181, v173, v175
	ds_bpermute_b32 v180, v173, v174
	v_mov_b64_e32 v[148:149], s[44:45]
	v_ashrrev_i32_e32 v183, 31, v182
	s_waitcnt lgkmcnt(2)
	v_pk_add_f32 v[176:177], v[176:177], v[178:179]
	s_waitcnt lgkmcnt(0)
	v_pk_add_f32 v[174:175], v[174:175], v[180:181]
	v_pk_fma_f32 v[176:177], v[176:177], s[22:23], v[148:149] op_sel_hi:[1,0,0]
	v_pk_fma_f32 v[174:175], v[174:175], s[22:23], v[148:149] op_sel_hi:[1,0,0]
	v_mul_f32_e32 v150, 0x4b800000, v177
	v_cmp_gt_f32_e32 vcc, s75, v177
	v_mul_f32_e32 v152, 0x4b800000, v176
	v_mul_f32_e32 v178, 0x4b800000, v175
	v_cndmask_b32_e32 v150, v177, v150, vcc
	v_mul_f32_e32 v179, 0x4b800000, v174
	v_cmp_gt_f32_e64 s[4:5], s75, v176
	v_cmp_gt_f32_e64 s[6:7], s75, v175
	v_cmp_gt_f32_e64 s[8:9], s75, v174
	v_rsq_f32_e32 v150, v150
	v_cndmask_b32_e64 v152, v176, v152, s[4:5]
	v_cndmask_b32_e64 v175, v175, v178, s[6:7]
	v_cndmask_b32_e64 v174, v174, v179, s[8:9]
	v_rsq_f32_e32 v152, v152
	v_rsq_f32_e32 v175, v175
	v_rsq_f32_e32 v177, v174
	v_mul_f32_e32 v174, 0x45800000, v150
	v_cndmask_b32_e32 v174, v150, v174, vcc
	v_mul_f32_e32 v176, 0x45800000, v152
	v_mul_f32_e32 v178, 0x45800000, v175
	v_mul_f32_e32 v179, 0x45800000, v177
	v_pk_mul_f32 v[124:125], v[124:125], v[174:175] op_sel_hi:[1,0]
	v_pk_mul_f32 v[126:127], v[126:127], v[174:175] op_sel_hi:[1,0]
	v_cndmask_b32_e64 v176, v152, v176, s[4:5]
	v_cndmask_b32_e64 v152, v175, v178, s[6:7]
	v_cndmask_b32_e64 v150, v177, v179, s[8:9]
	v_pk_mul_f32 v[120:121], v[120:121], v[174:175] op_sel_hi:[1,0]
	v_pk_mul_f32 v[122:123], v[122:123], v[174:175] op_sel_hi:[1,0]
	v_pk_mul_f32 v[116:117], v[116:117], v[174:175] op_sel_hi:[1,0]
	v_mul_f32_e32 v175, 0xbfb8aa3b, v124
	v_mul_f32_e32 v178, 0xbfb8aa3b, v126
	v_mul_f32_e32 v179, 0xbfb8aa3b, v127
	v_exp_f32_e32 v175, v175
	v_exp_f32_e32 v178, v178
	v_exp_f32_e32 v179, v179
	v_mul_f32_e32 v177, 0xbfb8aa3b, v125
	v_mul_f32_e32 v184, 0xbfb8aa3b, v116
	v_exp_f32_e32 v177, v177
	v_add_f32_e32 v175, 1.0, v175
	v_add_f32_e32 v180, 1.0, v178
	v_add_f32_e32 v181, 1.0, v179
	v_rcp_f32_e32 v178, v175
	v_rcp_f32_e32 v180, v180
	v_rcp_f32_e32 v181, v181
	v_exp_f32_e32 v175, v184
	v_add_f32_e32 v177, 1.0, v177
	v_mul_f32_e32 v185, 0xbfb8aa3b, v117
	v_rcp_f32_e32 v179, v177
	v_pk_mul_f32 v[126:127], v[126:127], v[180:181]
	v_pk_mul_f32 v[118:119], v[118:119], v[174:175] op_sel_hi:[1,0]
	v_exp_f32_e32 v177, v185
	v_pk_mul_f32 v[122:123], v[122:123], v[126:127]
	v_mul_f32_e32 v126, 0xbfb8aa3b, v118
	v_mul_f32_e32 v127, 0xbfb8aa3b, v119
	v_exp_f32_e32 v126, v126
	v_exp_f32_e32 v127, v127
	v_pk_mul_f32 v[124:125], v[124:125], v[178:179]
	v_pk_mul_f32 v[112:113], v[112:113], v[174:175] op_sel_hi:[1,0]
	v_pk_mul_f32 v[120:121], v[120:121], v[124:125]
	v_add_f32_e32 v124, 1.0, v175
; __device__ __forceinline__ unsigned pk2(float lo, float hi) { f32x2_t v = {lo, hi}; bf16x2_t b = __builtin_convertvector(v, bf16x2_t); return __builtin_bit_cast(unsigned, b); }
; __device__ __forceinline__ float sigm(float x) { return frcp(1.f + fexp2(-LOG2E * x)); }
;   __device__ __forceinline__ void operator()(const pg8::f32x4 (&acc)[2][2][4][2], const pg8::Unit& u, int wr, int wc, int fr, int fq) const {
;     ...
;       for (int m = 0; m < 4; ++m) {
;         const float r = rs[m]; float v[8];
; #pragma unroll
;         for (int n = 0; n < 2; ++n)
; #pragma unroll
;           for (int c = 0; c < 4; ++c) { const float g = acc[ai][0][m][n][c] * r, uu = acc[ai][1][m][n][c] * r; v[4 * n + c] = g * sigm(g) * uu; }
;         u32x4 w; w.x = pk2(v[0], v[1]); w.y = pk2(v[2], v[3]); w.z = pk2(v[4], v[5]); w.w = pk2(v[6], v[7]);
;         *(u32x4*)(hbuf + (unsigned)(row0 + ai * 128 + m * 16) * DFF + col0) = w;
;       }
	v_add_f32_e32 v125, 1.0, v177
	v_rcp_f32_e32 v124, v124
	v_rcp_f32_e32 v125, v125
	v_add_f32_e32 v126, 1.0, v126
	v_add_f32_e32 v127, 1.0, v127
	v_rcp_f32_e32 v126, v126
	v_rcp_f32_e32 v127, v127
	v_pk_mul_f32 v[116:117], v[116:117], v[124:125]
	v_pk_mul_f32 v[114:115], v[114:115], v[174:175] op_sel_hi:[1,0]
	v_pk_mul_f32 v[112:113], v[112:113], v[116:117]
	v_pk_mul_f32 v[116:117], v[118:119], v[126:127]
	v_cvt_pk_bf16_f32 v118, v112, v113
	v_pk_mul_f32 v[114:115], v[114:115], v[116:117]
	v_cvt_pk_bf16_f32 v116, v120, v121
	v_cvt_pk_bf16_f32 v119, v114, v115
	v_mul_lo_u32 v114, v190, s76
	v_mov_b32_e32 v115, v137
	v_lshl_add_u64 v[120:121], v[114:115], 1, s[38:39]
	v_lshlrev_b64 v[112:113], 1, v[182:183]
	v_pk_mul_f32 v[108:109], v[108:109], v[176:177] op_sel_hi:[1,0]
	v_cvt_pk_bf16_f32 v117, v122, v123
	v_lshl_add_u64 v[120:121], v[120:121], 0, v[112:113]
	v_mul_f32_e32 v115, 0xbfb8aa3b, v108
	v_exp_f32_e32 v115, v115
	global_store_dwordx4 v[120:121], v[116:119], off
	v_pk_mul_f32 v[110:111], v[110:111], v[176:177] op_sel_hi:[1,0]
	v_pk_mul_f32 v[100:101], v[100:101], v[176:177] op_sel_hi:[1,0]
	v_mul_f32_e32 v116, 0xbfb8aa3b, v109
	v_exp_f32_e32 v117, v116
	v_add_f32_e32 v115, 1.0, v115
	v_rcp_f32_e32 v116, v115
	v_pk_mul_f32 v[104:105], v[104:105], v[176:177] op_sel_hi:[1,0]
	v_add_f32_e32 v115, 1.0, v117
	v_mul_f32_e32 v117, 0xbfb8aa3b, v110
	v_exp_f32_e32 v118, v117
	v_mul_f32_e32 v117, 0xbfb8aa3b, v111
	v_exp_f32_e32 v119, v117
	v_rcp_f32_e32 v117, v115
	v_add_f32_e32 v115, 1.0, v118
	v_rcp_f32_e32 v118, v115
	v_add_f32_e32 v115, 1.0, v119
	v_rcp_f32_e32 v119, v115
	v_pk_mul_f32 v[108:109], v[108:109], v[116:117]
	v_pk_mul_f32 v[102:103], v[102:103], v[176:177] op_sel_hi:[1,0]
	v_pk_mul_f32 v[100:101], v[100:101], v[108:109]
	v_pk_mul_f32 v[108:109], v[110:111], v[118:119]
	v_mul_f32_e32 v110, 0xbfb8aa3b, v104
	v_exp_f32_e32 v110, v110
	v_pk_mul_f32 v[102:103], v[102:103], v[108:109]
	v_mul_f32_e32 v108, 0xbfb8aa3b, v105
	v_pk_mul_f32 v[106:107], v[106:107], v[176:177] op_sel_hi:[1,0]
	v_exp_f32_e32 v109, v108
	v_add_f32_e32 v108, 1.0, v110
	v_mul_f32_e32 v110, 0xbfb8aa3b, v106
	v_mul_f32_e32 v111, 0xbfb8aa3b, v107
	v_exp_f32_e32 v110, v110
	v_exp_f32_e32 v111, v111
	v_add_f32_e32 v109, 1.0, v109
	v_rcp_f32_e32 v108, v108
	v_rcp_f32_e32 v109, v109
	v_add_f32_e32 v110, 1.0, v110
	v_add_f32_e32 v111, 1.0, v111
	v_rcp_f32_e32 v110, v110
	v_rcp_f32_e32 v111, v111
	v_pk_mul_f32 v[96:97], v[96:97], v[176:177] op_sel_hi:[1,0]
	v_pk_mul_f32 v[104:105], v[104:105], v[108:109]
	v_pk_mul_f32 v[92:93], v[92:93], v[152:153] op_sel_hi:[1,0]
	v_pk_mul_f32 v[104:105], v[96:97], v[104:105]
	v_pk_mul_f32 v[96:97], v[98:99], v[176:177] op_sel_hi:[1,0]
	v_pk_mul_f32 v[98:99], v[106:107], v[110:111]
	v_pk_mul_f32 v[94:95], v[94:95], v[152:153] op_sel_hi:[1,0]
	v_pk_mul_f32 v[106:107], v[96:97], v[98:99]
	v_cvt_pk_bf16_f32 v96, v100, v101
	v_add_u32_e32 v100, 0xb000, v114
	v_mov_b32_e32 v101, v137
	v_lshl_add_u64 v[100:101], v[100:101], 1, s[38:39]
	v_cvt_pk_bf16_f32 v97, v102, v103
	v_cvt_pk_bf16_f32 v98, v104, v105
	v_cvt_pk_bf16_f32 v99, v106, v107
	v_lshl_add_u64 v[100:101], v[100:101], 0, v[112:113]
	v_mul_f32_e32 v102, 0xbfb8aa3b, v92
	global_store_dwordx4 v[100:101], v[96:99], off
	v_exp_f32_e32 v102, v102
	v_pk_mul_f32 v[84:85], v[84:85], v[152:153] op_sel_hi:[1,0]
	v_mul_f32_e32 v96, 0xbfb8aa3b, v93
	v_exp_f32_e32 v97, v96
	v_mul_f32_e32 v98, 0xbfb8aa3b, v94
	v_mul_f32_e32 v99, 0xbfb8aa3b, v95
	v_exp_f32_e32 v98, v98
	v_exp_f32_e32 v99, v99
	v_add_f32_e32 v96, 1.0, v102
	v_add_f32_e32 v97, 1.0, v97
	v_rcp_f32_e32 v96, v96
	v_rcp_f32_e32 v97, v97
	v_add_f32_e32 v98, 1.0, v98
	v_add_f32_e32 v99, 1.0, v99
	v_rcp_f32_e32 v98, v98
	v_rcp_f32_e32 v99, v99
	v_pk_mul_f32 v[92:93], v[92:93], v[96:97]
	v_pk_mul_f32 v[88:89], v[88:89], v[152:153] op_sel_hi:[1,0]
	v_pk_mul_f32 v[84:85], v[84:85], v[92:93]
	v_pk_mul_f32 v[92:93], v[94:95], v[98:99]
	v_mul_f32_e32 v94, 0xbfb8aa3b, v88
	v_exp_f32_e32 v94, v94
	v_pk_mul_f32 v[86:87], v[86:87], v[152:153] op_sel_hi:[1,0]
	v_pk_mul_f32 v[90:91], v[90:91], v[152:153] op_sel_hi:[1,0]
	v_pk_mul_f32 v[86:87], v[86:87], v[92:93]
	v_mul_f32_e32 v92, 0xbfb8aa3b, v89
	v_exp_f32_e32 v93, v92
	v_add_f32_e32 v92, 1.0, v94
	v_mul_f32_e32 v94, 0xbfb8aa3b, v90
	v_mul_f32_e32 v95, 0xbfb8aa3b, v91
	v_exp_f32_e32 v94, v94
	v_exp_f32_e32 v95, v95
	v_add_f32_e32 v93, 1.0, v93
	v_rcp_f32_e32 v92, v92
	v_rcp_f32_e32 v93, v93
	v_add_f32_e32 v94, 1.0, v94
	v_add_f32_e32 v95, 1.0, v95
	v_rcp_f32_e32 v94, v94
	v_rcp_f32_e32 v95, v95
	v_pk_mul_f32 v[80:81], v[80:81], v[152:153] op_sel_hi:[1,0]
	v_pk_mul_f32 v[88:89], v[88:89], v[92:93]
	v_pk_mul_f32 v[76:77], v[76:77], v[150:151] op_sel_hi:[1,0]
	v_pk_mul_f32 v[88:89], v[80:81], v[88:89]
	v_pk_mul_f32 v[80:81], v[82:83], v[152:153] op_sel_hi:[1,0]
	v_pk_mul_f32 v[82:83], v[90:91], v[94:95]
	v_pk_mul_f32 v[78:79], v[78:79], v[150:151] op_sel_hi:[1,0]
	v_pk_mul_f32 v[90:91], v[80:81], v[82:83]
	v_cvt_pk_bf16_f32 v80, v84, v85
	v_add_u32_e32 v84, 0x16000, v114
	v_mov_b32_e32 v85, v137
	v_lshl_add_u64 v[84:85], v[84:85], 1, s[38:39]
	v_cvt_pk_bf16_f32 v81, v86, v87
	v_cvt_pk_bf16_f32 v82, v88, v89
	v_cvt_pk_bf16_f32 v83, v90, v91
	v_lshl_add_u64 v[84:85], v[84:85], 0, v[112:113]
	v_mul_f32_e32 v86, 0xbfb8aa3b, v76
	global_store_dwordx4 v[84:85], v[80:83], off
	v_exp_f32_e32 v86, v86
	v_pk_mul_f32 v[68:69], v[68:69], v[150:151] op_sel_hi:[1,0]
	v_mul_f32_e32 v80, 0xbfb8aa3b, v77
	v_exp_f32_e32 v81, v80
	v_mul_f32_e32 v82, 0xbfb8aa3b, v78
	v_mul_f32_e32 v83, 0xbfb8aa3b, v79
	v_exp_f32_e32 v82, v82
	v_exp_f32_e32 v83, v83
	v_add_f32_e32 v80, 1.0, v86
	v_add_f32_e32 v81, 1.0, v81
; __device__ __forceinline__ unsigned pk2(float lo, float hi) { f32x2_t v = {lo, hi}; bf16x2_t b = __builtin_convertvector(v, bf16x2_t); return __builtin_bit_cast(unsigned, b); }
; __device__ __forceinline__ float sigm(float x) { return frcp(1.f + fexp2(-LOG2E * x)); }
;   __device__ __forceinline__ void operator()(const pg8::f32x4 (&acc)[2][2][4][2], const pg8::Unit& u, int wr, int wc, int fr, int fq) const {
;     ...
;       for (int m = 0; m < 4; ++m) { const f32x4 a = *(const f32x4*)(ssq + (unsigned)(row0 + ai * 128 + m * 16) * 16 + 4 * fq); rs[m] = (a[0] + a[1]) + (a[2] + a[3]); }
; #pragma unroll
;       for (int m = 0; m < 4; ++m) { float v = rs[m]; v += __shfl_xor(v, 16); v += __shfl_xor(v, 32); rs[m] = rsqrtf(v * (1.f / 1024.f) + EPS); }
; #pragma unroll
;       for (int m = 0; m < 4; ++m) {
;         const float r = rs[m]; float v[8];
; #pragma unroll
;         for (int n = 0; n < 2; ++n)
; #pragma unroll
;           for (int c = 0; c < 4; ++c) { const float g = acc[ai][0][m][n][c] * r, uu = acc[ai][1][m][n][c] * r; v[4 * n + c] = g * sigm(g) * uu; }
;         u32x4 w; w.x = pk2(v[0], v[1]); w.y = pk2(v[2], v[3]); w.z = pk2(v[4], v[5]); w.w = pk2(v[6], v[7]);
;         *(u32x4*)(hbuf + (unsigned)(row0 + ai * 128 + m * 16) * DFF + col0) = w;
;       }
	v_rcp_f32_e32 v80, v80
	v_rcp_f32_e32 v81, v81
	v_add_f32_e32 v82, 1.0, v82
	v_add_f32_e32 v83, 1.0, v83
	v_rcp_f32_e32 v82, v82
	v_rcp_f32_e32 v83, v83
	v_pk_mul_f32 v[76:77], v[76:77], v[80:81]
	v_pk_mul_f32 v[72:73], v[72:73], v[150:151] op_sel_hi:[1,0]
	v_pk_mul_f32 v[68:69], v[68:69], v[76:77]
	v_pk_mul_f32 v[76:77], v[78:79], v[82:83]
	v_mul_f32_e32 v78, 0xbfb8aa3b, v72
	v_exp_f32_e32 v78, v78
	v_pk_mul_f32 v[70:71], v[70:71], v[150:151] op_sel_hi:[1,0]
	v_pk_mul_f32 v[74:75], v[74:75], v[150:151] op_sel_hi:[1,0]
	v_pk_mul_f32 v[70:71], v[70:71], v[76:77]
	v_mul_f32_e32 v76, 0xbfb8aa3b, v73
	v_exp_f32_e32 v77, v76
	v_add_f32_e32 v76, 1.0, v78
	v_mul_f32_e32 v78, 0xbfb8aa3b, v74
	v_mul_f32_e32 v79, 0xbfb8aa3b, v75
	v_exp_f32_e32 v78, v78
	v_exp_f32_e32 v79, v79
	v_add_f32_e32 v77, 1.0, v77
	v_rcp_f32_e32 v76, v76
	v_rcp_f32_e32 v77, v77
	v_add_f32_e32 v78, 1.0, v78
	v_add_f32_e32 v79, 1.0, v79
	v_rcp_f32_e32 v78, v78
	v_rcp_f32_e32 v79, v79
	v_pk_mul_f32 v[64:65], v[64:65], v[150:151] op_sel_hi:[1,0]
	v_pk_mul_f32 v[72:73], v[72:73], v[76:77]
	s_nop 0
	v_pk_mul_f32 v[72:73], v[64:65], v[72:73]
	v_pk_mul_f32 v[64:65], v[66:67], v[150:151] op_sel_hi:[1,0]
	v_pk_mul_f32 v[66:67], v[74:75], v[78:79]
	s_nop 0
	v_pk_mul_f32 v[74:75], v[64:65], v[66:67]
	v_cvt_pk_bf16_f32 v64, v68, v69
	v_add_u32_e32 v68, 0x21000, v114
	v_mov_b32_e32 v69, v137
	v_lshl_add_u64 v[68:69], v[68:69], 1, s[38:39]
	v_cvt_pk_bf16_f32 v65, v70, v71
	v_cvt_pk_bf16_f32 v66, v72, v73
	v_cvt_pk_bf16_f32 v67, v74, v75
	v_lshl_add_u64 v[68:69], v[68:69], 0, v[112:113]
	global_store_dwordx4 v[68:69], v[64:67], off
	v_add_u32_e32 v136, 0x58000, v114
	v_mov_b64_e32 v[72:73], v[208:209]
	v_mov_b64_e32 v[74:75], v[210:211]
	v_mov_b64_e32 v[76:77], v[212:213]
	v_mov_b64_e32 v[78:79], v[214:215]
	v_mov_b64_e32 v[64:65], v[200:201]
	v_mov_b64_e32 v[66:67], v[202:203]
	v_mov_b64_e32 v[68:69], v[204:205]
	v_mov_b64_e32 v[70:71], v[206:207]
	v_mov_b32_e32 v80, v65
	v_mov_b32_e32 v81, v66
	v_mov_b32_e32 v65, v67
	v_mov_b32_e32 v66, v69
	v_mov_b32_e32 v67, v70
	v_mov_b32_e32 v69, v71
	v_pk_add_f32 v[64:65], v[80:81], v[64:65]
	v_pk_add_f32 v[66:67], v[66:67], v[68:69]
	v_mov_b32_e32 v69, v64
	v_mov_b32_e32 v68, v66
	v_mov_b32_e32 v64, v67
	v_pk_add_f32 v[64:65], v[68:69], v[64:65]
	ds_bpermute_b32 v67, v172, v65
	ds_bpermute_b32 v66, v172, v64
	v_mov_b32_e32 v68, v73
	v_mov_b32_e32 v69, v74
	v_mov_b32_e32 v73, v75
	v_mov_b32_e32 v70, v77
	s_waitcnt lgkmcnt(0)
	v_pk_add_f32 v[64:65], v[64:65], v[66:67]
	ds_bpermute_b32 v67, v173, v65
	ds_bpermute_b32 v66, v173, v64
	v_mov_b32_e32 v71, v78
	v_mov_b32_e32 v77, v79
	v_pk_add_f32 v[68:69], v[68:69], v[72:73]
	v_pk_add_f32 v[70:71], v[70:71], v[76:77]
	s_waitcnt lgkmcnt(0)
	v_pk_add_f32 v[64:65], v[64:65], v[66:67]
	v_mov_b32_e32 v67, v68
	v_pk_fma_f32 v[64:65], v[64:65], s[22:23], v[148:149] op_sel_hi:[1,0,0]
	v_mov_b32_e32 v68, v71
	v_mul_f32_e32 v66, 0x4b800000, v65
	v_cmp_gt_f32_e32 vcc, s75, v65
	v_cmp_gt_f32_e64 s[4:5], s75, v64
	s_nop 0
	v_cndmask_b32_e32 v65, v65, v66, vcc
	v_mov_b32_e32 v66, v70
	v_pk_add_f32 v[66:67], v[66:67], v[68:69]
	ds_bpermute_b32 v69, v172, v67
	ds_bpermute_b32 v68, v172, v66
	v_rsq_f32_e32 v72, v65
	v_mul_f32_e32 v65, 0x4b800000, v64
	v_cndmask_b32_e64 v64, v64, v65, s[4:5]
	v_rsq_f32_e32 v70, v64
	s_waitcnt lgkmcnt(0)
	v_pk_add_f32 v[64:65], v[66:67], v[68:69]
	ds_bpermute_b32 v67, v173, v65
	ds_bpermute_b32 v66, v173, v64
	v_mul_f32_e32 v68, 0x45800000, v72
	v_cndmask_b32_e32 v68, v72, v68, vcc
	v_mul_f32_e32 v69, 0x45800000, v70
	v_pk_mul_f32 v[62:63], v[62:63], v[68:69] op_sel_hi:[1,0]
	s_waitcnt lgkmcnt(0)
	v_pk_add_f32 v[64:65], v[64:65], v[66:67]
	v_pk_mul_f32 v[56:57], v[56:57], v[68:69] op_sel_hi:[1,0]
	v_pk_fma_f32 v[64:65], v[64:65], s[22:23], v[148:149] op_sel_hi:[1,0,0]
	v_pk_mul_f32 v[54:55], v[54:55], v[68:69] op_sel_hi:[1,0]
	v_mul_f32_e32 v66, 0x4b800000, v65
	v_cmp_gt_f32_e32 vcc, s75, v65
	v_cmp_gt_f32_e64 s[6:7], s75, v64
	v_pk_mul_f32 v[58:59], v[58:59], v[68:69] op_sel_hi:[1,0]
	v_cndmask_b32_e32 v65, v65, v66, vcc
	v_mul_f32_e32 v66, 0x4b800000, v64
	v_rsq_f32_e32 v65, v65
	v_cndmask_b32_e64 v64, v64, v66, s[6:7]
	v_rsq_f32_e32 v67, v64
	v_cndmask_b32_e64 v66, v70, v69, s[4:5]
	v_mul_f32_e32 v64, 0x45800000, v65
	v_pk_mul_f32 v[70:71], v[60:61], v[68:69] op_sel_hi:[1,0]
	v_cndmask_b32_e32 v64, v65, v64, vcc
	v_mul_f32_e32 v65, 0x45800000, v67
	v_mul_f32_e32 v60, 0xbfb8aa3b, v70
	v_exp_f32_e32 v61, v60
	v_cndmask_b32_e64 v60, v67, v65, s[6:7]
	v_mul_f32_e32 v65, 0xbfb8aa3b, v71
	v_exp_f32_e32 v65, v65
	v_add_f32_e32 v61, 1.0, v61
	v_rcp_f32_e32 v72, v61
	v_mul_f32_e32 v67, 0xbfb8aa3b, v63
	v_add_f32_e32 v61, 1.0, v65
	v_mul_f32_e32 v65, 0xbfb8aa3b, v62
	v_exp_f32_e32 v65, v65
	v_exp_f32_e32 v67, v67
	v_rcp_f32_e32 v73, v61
	v_pk_mul_f32 v[52:53], v[52:53], v[68:69] op_sel_hi:[1,0]
	v_add_f32_e32 v61, 1.0, v65
	v_rcp_f32_e32 v74, v61
	v_add_f32_e32 v61, 1.0, v67
	v_rcp_f32_e32 v75, v61
	v_mul_f32_e32 v61, 0xbfb8aa3b, v56
	v_exp_f32_e32 v61, v61
	v_pk_mul_f32 v[70:71], v[70:71], v[72:73]
	v_pk_mul_f32 v[62:63], v[62:63], v[74:75]
	v_pk_mul_f32 v[52:53], v[52:53], v[70:71]
	v_pk_mul_f32 v[54:55], v[54:55], v[62:63]
	v_mul_f32_e32 v62, 0xbfb8aa3b, v57
	v_exp_f32_e32 v63, v62
	v_add_f32_e32 v61, 1.0, v61
	v_rcp_f32_e32 v62, v61
	v_pk_mul_f32 v[48:49], v[48:49], v[68:69] op_sel_hi:[1,0]
	v_add_f32_e32 v61, 1.0, v63
	v_mul_f32_e32 v63, 0xbfb8aa3b, v58
	v_exp_f32_e32 v65, v63
	v_mul_f32_e32 v63, 0xbfb8aa3b, v59
	v_exp_f32_e32 v67, v63
	v_rcp_f32_e32 v63, v61
	v_add_f32_e32 v61, 1.0, v65
	v_rcp_f32_e32 v70, v61
	v_add_f32_e32 v61, 1.0, v67
	v_rcp_f32_e32 v71, v61
	v_pk_mul_f32 v[56:57], v[56:57], v[62:63]
; __device__ __forceinline__ unsigned pk2(float lo, float hi) { f32x2_t v = {lo, hi}; bf16x2_t b = __builtin_convertvector(v, bf16x2_t); return __builtin_bit_cast(unsigned, b); }
; __device__ __forceinline__ float sigm(float x) { return frcp(1.f + fexp2(-LOG2E * x)); }
; #define PG8_BAR __builtin_amdgcn_s_barrier()
; template <class Epi, class Sched, bool ALIGN_EPI = false, bool SP2 = false, bool F16 = false, bool TOKPERM = false>
; __device__ __forceinline__ void gemm_phase(PG8_LAS unsigned char* lds, const Gemm g, const Sched& S, const Epi& E, int wv) {
;     ...
;         if constexpr (ALIGN_EPI) { if (wr == 0) PG8_BAR; }
;         if constexpr (!Epi::AFTER_DRAIN) { E(acc, cur, wr, wc, fr, fq); S.done(cur); }
;         if (!has_next) break;
; #pragma unroll
;         for (int a = 0; a < 2; ++a)
; #pragma unroll
;             for (int b = 0; b < 2; ++b)
; #pragma unroll
;                 for (int m = 0; m < 4; ++m)
; #pragma unroll
;                     for (int n = 0; n < 2; ++n) acc[a][b][m][n] = (f32x4){0.f, 0.f, 0.f, 0.f};
;         cur = nxt; cA = nA; cB = nB; ++ui;
;         if constexpr (ALIGN_EPI) { if (wr == 1) PG8_BAR; }
;   __device__ __forceinline__ void operator()(const pg8::f32x4 (&acc)[2][2][4][2], const pg8::Unit& u, int wr, int wc, int fr, int fq) const {
;     ...
;       for (int m = 0; m < 4; ++m) {
;         const float r = rs[m]; float v[8];
; #pragma unroll
;         for (int n = 0; n < 2; ++n)
; #pragma unroll
;           for (int c = 0; c < 4; ++c) { const float g = acc[ai][0][m][n][c] * r, uu = acc[ai][1][m][n][c] * r; v[4 * n + c] = g * sigm(g) * uu; }
;         u32x4 w; w.x = pk2(v[0], v[1]); w.y = pk2(v[2], v[3]); w.z = pk2(v[4], v[5]); w.w = pk2(v[6], v[7]);
;         *(u32x4*)(hbuf + (unsigned)(row0 + ai * 128 + m * 16) * DFF + col0) = w;
;       }
	v_pk_mul_f32 v[44:45], v[44:45], v[66:67] op_sel_hi:[1,0]
	v_pk_mul_f32 v[56:57], v[48:49], v[56:57]
	v_pk_mul_f32 v[48:49], v[50:51], v[68:69] op_sel_hi:[1,0]
	v_pk_mul_f32 v[50:51], v[58:59], v[70:71]
	v_pk_mul_f32 v[46:47], v[46:47], v[66:67] op_sel_hi:[1,0]
	v_pk_mul_f32 v[58:59], v[48:49], v[50:51]
	v_cvt_pk_bf16_f32 v48, v52, v53
	v_lshl_add_u64 v[52:53], v[136:137], 1, s[38:39]
	v_cvt_pk_bf16_f32 v49, v54, v55
	v_cvt_pk_bf16_f32 v50, v56, v57
	v_cvt_pk_bf16_f32 v51, v58, v59
	v_lshl_add_u64 v[52:53], v[52:53], 0, v[112:113]
	v_mul_f32_e32 v54, 0xbfb8aa3b, v44
	global_store_dwordx4 v[52:53], v[48:51], off
	v_exp_f32_e32 v54, v54
	v_pk_mul_f32 v[36:37], v[36:37], v[66:67] op_sel_hi:[1,0]
	v_mul_f32_e32 v48, 0xbfb8aa3b, v45
	v_exp_f32_e32 v49, v48
	v_mul_f32_e32 v50, 0xbfb8aa3b, v46
	v_mul_f32_e32 v51, 0xbfb8aa3b, v47
	v_exp_f32_e32 v50, v50
	v_exp_f32_e32 v51, v51
	v_add_f32_e32 v48, 1.0, v54
	v_add_f32_e32 v49, 1.0, v49
	v_rcp_f32_e32 v48, v48
	v_rcp_f32_e32 v49, v49
	v_add_f32_e32 v50, 1.0, v50
	v_add_f32_e32 v51, 1.0, v51
	v_rcp_f32_e32 v50, v50
	v_rcp_f32_e32 v51, v51
	v_pk_mul_f32 v[44:45], v[44:45], v[48:49]
	v_pk_mul_f32 v[40:41], v[40:41], v[66:67] op_sel_hi:[1,0]
	v_pk_mul_f32 v[36:37], v[36:37], v[44:45]
	v_pk_mul_f32 v[44:45], v[46:47], v[50:51]
	v_mul_f32_e32 v46, 0xbfb8aa3b, v40
	v_exp_f32_e32 v46, v46
	v_pk_mul_f32 v[38:39], v[38:39], v[66:67] op_sel_hi:[1,0]
	v_pk_mul_f32 v[42:43], v[42:43], v[66:67] op_sel_hi:[1,0]
	v_pk_mul_f32 v[38:39], v[38:39], v[44:45]
	v_mul_f32_e32 v44, 0xbfb8aa3b, v41
	v_exp_f32_e32 v45, v44
	v_add_f32_e32 v44, 1.0, v46
	v_mul_f32_e32 v46, 0xbfb8aa3b, v42
	v_mul_f32_e32 v47, 0xbfb8aa3b, v43
	v_exp_f32_e32 v46, v46
	v_exp_f32_e32 v47, v47
	v_add_f32_e32 v45, 1.0, v45
	v_rcp_f32_e32 v44, v44
	v_rcp_f32_e32 v45, v45
	v_add_f32_e32 v46, 1.0, v46
	v_add_f32_e32 v47, 1.0, v47
	v_rcp_f32_e32 v46, v46
	v_rcp_f32_e32 v47, v47
	v_pk_mul_f32 v[32:33], v[32:33], v[66:67] op_sel_hi:[1,0]
	v_pk_mul_f32 v[40:41], v[40:41], v[44:45]
	v_add_u32_e32 v136, 0x63000, v114
	v_pk_mul_f32 v[40:41], v[32:33], v[40:41]
	v_pk_mul_f32 v[32:33], v[34:35], v[66:67] op_sel_hi:[1,0]
	v_pk_mul_f32 v[34:35], v[42:43], v[46:47]
	v_pk_mul_f32 v[28:29], v[28:29], v[64:65] op_sel_hi:[1,0]
	v_pk_mul_f32 v[42:43], v[32:33], v[34:35]
	v_cvt_pk_bf16_f32 v32, v36, v37
	v_lshl_add_u64 v[36:37], v[136:137], 1, s[38:39]
	v_cvt_pk_bf16_f32 v33, v38, v39
	v_cvt_pk_bf16_f32 v34, v40, v41
	v_cvt_pk_bf16_f32 v35, v42, v43
	v_lshl_add_u64 v[36:37], v[36:37], 0, v[112:113]
	v_mul_f32_e32 v38, 0xbfb8aa3b, v28
	global_store_dwordx4 v[36:37], v[32:35], off
	v_pk_mul_f32 v[30:31], v[30:31], v[64:65] op_sel_hi:[1,0]
	v_exp_f32_e32 v38, v38
	v_mul_f32_e32 v32, 0xbfb8aa3b, v29
	v_exp_f32_e32 v33, v32
	v_mul_f32_e32 v34, 0xbfb8aa3b, v30
	v_mul_f32_e32 v35, 0xbfb8aa3b, v31
	v_exp_f32_e32 v34, v34
	v_exp_f32_e32 v35, v35
	v_add_f32_e32 v32, 1.0, v38
	v_add_f32_e32 v33, 1.0, v33
	v_rcp_f32_e32 v32, v32
	v_rcp_f32_e32 v33, v33
	v_add_f32_e32 v34, 1.0, v34
	v_add_f32_e32 v35, 1.0, v35
	v_rcp_f32_e32 v34, v34
	v_rcp_f32_e32 v35, v35
	v_pk_mul_f32 v[20:21], v[20:21], v[64:65] op_sel_hi:[1,0]
	v_pk_mul_f32 v[28:29], v[28:29], v[32:33]
	v_pk_mul_f32 v[24:25], v[24:25], v[64:65] op_sel_hi:[1,0]
	v_pk_mul_f32 v[20:21], v[20:21], v[28:29]
	v_pk_mul_f32 v[28:29], v[30:31], v[34:35]
	v_mul_f32_e32 v30, 0xbfb8aa3b, v24
	v_exp_f32_e32 v30, v30
	v_pk_mul_f32 v[22:23], v[22:23], v[64:65] op_sel_hi:[1,0]
	v_pk_mul_f32 v[26:27], v[26:27], v[64:65] op_sel_hi:[1,0]
	v_pk_mul_f32 v[22:23], v[22:23], v[28:29]
	v_mul_f32_e32 v28, 0xbfb8aa3b, v25
	v_exp_f32_e32 v29, v28
	v_add_f32_e32 v28, 1.0, v30
	v_mul_f32_e32 v30, 0xbfb8aa3b, v26
	v_mul_f32_e32 v31, 0xbfb8aa3b, v27
	v_exp_f32_e32 v30, v30
	v_exp_f32_e32 v31, v31
	v_add_f32_e32 v29, 1.0, v29
	v_rcp_f32_e32 v28, v28
	v_rcp_f32_e32 v29, v29
	v_add_f32_e32 v30, 1.0, v30
	v_add_f32_e32 v31, 1.0, v31
	v_rcp_f32_e32 v30, v30
	v_rcp_f32_e32 v31, v31
	v_pk_mul_f32 v[16:17], v[16:17], v[64:65] op_sel_hi:[1,0]
	v_pk_mul_f32 v[24:25], v[24:25], v[28:29]
	v_add_u32_e32 v136, 0x6e000, v114
	v_pk_mul_f32 v[24:25], v[16:17], v[24:25]
	v_pk_mul_f32 v[16:17], v[18:19], v[64:65] op_sel_hi:[1,0]
	v_pk_mul_f32 v[18:19], v[26:27], v[30:31]
	v_pk_mul_f32 v[12:13], v[12:13], v[60:61] op_sel_hi:[1,0]
	v_pk_mul_f32 v[26:27], v[16:17], v[18:19]
	v_cvt_pk_bf16_f32 v16, v20, v21
	v_lshl_add_u64 v[20:21], v[136:137], 1, s[38:39]
	v_cvt_pk_bf16_f32 v17, v22, v23
	v_cvt_pk_bf16_f32 v18, v24, v25
	v_cvt_pk_bf16_f32 v19, v26, v27
	v_lshl_add_u64 v[20:21], v[20:21], 0, v[112:113]
	v_mul_f32_e32 v22, 0xbfb8aa3b, v12
	global_store_dwordx4 v[20:21], v[16:19], off
	v_pk_mul_f32 v[14:15], v[14:15], v[60:61] op_sel_hi:[1,0]
	v_exp_f32_e32 v22, v22
	v_mul_f32_e32 v16, 0xbfb8aa3b, v13
	v_exp_f32_e32 v17, v16
	v_mul_f32_e32 v18, 0xbfb8aa3b, v14
	v_mul_f32_e32 v19, 0xbfb8aa3b, v15
	v_exp_f32_e32 v18, v18
	v_exp_f32_e32 v19, v19
	v_add_f32_e32 v16, 1.0, v22
	v_add_f32_e32 v17, 1.0, v17
	v_rcp_f32_e32 v16, v16
	v_rcp_f32_e32 v17, v17
	v_add_f32_e32 v18, 1.0, v18
	v_add_f32_e32 v19, 1.0, v19
	v_rcp_f32_e32 v18, v18
	v_rcp_f32_e32 v19, v19
	v_pk_mul_f32 v[4:5], v[4:5], v[60:61] op_sel_hi:[1,0]
	v_pk_mul_f32 v[12:13], v[12:13], v[16:17]
	v_pk_mul_f32 v[8:9], v[8:9], v[60:61] op_sel_hi:[1,0]
	v_pk_mul_f32 v[4:5], v[4:5], v[12:13]
	v_pk_mul_f32 v[12:13], v[14:15], v[18:19]
	v_mul_f32_e32 v14, 0xbfb8aa3b, v8
	v_exp_f32_e32 v14, v14
	v_pk_mul_f32 v[6:7], v[6:7], v[60:61] op_sel_hi:[1,0]
	v_pk_mul_f32 v[10:11], v[10:11], v[60:61] op_sel_hi:[1,0]
	v_pk_mul_f32 v[6:7], v[6:7], v[12:13]
	v_mul_f32_e32 v12, 0xbfb8aa3b, v9
	v_exp_f32_e32 v13, v12
	v_add_f32_e32 v12, 1.0, v14
	v_mul_f32_e32 v14, 0xbfb8aa3b, v10
	v_mul_f32_e32 v15, 0xbfb8aa3b, v11
	v_exp_f32_e32 v14, v14
	v_exp_f32_e32 v15, v15
	v_add_f32_e32 v13, 1.0, v13
	v_rcp_f32_e32 v12, v12
	v_rcp_f32_e32 v13, v13
	v_add_f32_e32 v14, 1.0, v14
	v_add_f32_e32 v15, 1.0, v15
	v_rcp_f32_e32 v14, v14
	v_rcp_f32_e32 v15, v15
	v_pk_mul_f32 v[0:1], v[0:1], v[60:61] op_sel_hi:[1,0]
	v_pk_mul_f32 v[8:9], v[8:9], v[12:13]
	v_add_u32_e32 v136, 0x79000, v114
	v_pk_mul_f32 v[8:9], v[0:1], v[8:9]
	v_pk_mul_f32 v[0:1], v[2:3], v[60:61] op_sel_hi:[1,0]
	v_pk_mul_f32 v[2:3], v[10:11], v[14:15]
	s_andn2_b64 vcc, exec, s[2:3]
	v_pk_mul_f32 v[10:11], v[0:1], v[2:3]
	v_cvt_pk_bf16_f32 v0, v4, v5
	v_lshl_add_u64 v[4:5], v[136:137], 1, s[38:39]
	v_cvt_pk_bf16_f32 v1, v6, v7
	v_cvt_pk_bf16_f32 v2, v8, v9
	v_cvt_pk_bf16_f32 v3, v10, v11
	v_lshl_add_u64 v[4:5], v[4:5], 0, v[112:113]
	global_store_dwordx4 v[4:5], v[0:3], off
	s_mov_b64 s[2:3], -1
	s_cbranch_vccnz .LBB0_177
	s_andn2_b64 vcc, exec, s[10:11]
	s_cbranch_vccnz .LBB0_176
	s_barrier
	s_branch .LBB0_176

; __device__ __forceinline__ unsigned pk2(float lo, float hi) { f32x2_t v = {lo, hi}; bf16x2_t b = __builtin_convertvector(v, bf16x2_t); return __builtin_bit_cast(unsigned, b); }
; __device__ __forceinline__ float sigm(float x) { return frcp(1.f + fexp2(-LOG2E * x)); }
;   __device__ __forceinline__ void operator()(const pg8::f32x4 (&acc)[2][2][4][2], const pg8::Unit& u, int wr, int wc, int fr, int fq) const {
;     int z; asm volatile("v_mov_b32 %0, 0" : "=v"(z));
;     const int row0 = u.pm * 256 + wr * 64 + fr + z, col0 = u.pn * 128 + wc * 32 + 8 * fq + z;
; #pragma unroll
;     for (int ai = 0; ai < 2; ++ai) {
;       float rs[4];
; #pragma unroll
;       for (int m = 0; m < 4; ++m) { const f32x4 a = *(const f32x4*)(ssq + (unsigned)(row0 + ai * 128 + m * 16) * 16 + 4 * fq); rs[m] = (a[0] + a[1]) + (a[2] + a[3]); }
; #pragma unroll
;       for (int m = 0; m < 4; ++m) { float v = rs[m]; v += __shfl_xor(v, 16); v += __shfl_xor(v, 32); rs[m] = rsqrtf(v * (1.f / 1024.f) + EPS); }
; #pragma unroll
;       for (int m = 0; m < 4; ++m) {
;         const float r = rs[m]; float v[8];
; #pragma unroll
;         for (int n = 0; n < 2; ++n)
; #pragma unroll
;           for (int c = 0; c < 4; ++c) { const float g = acc[ai][0][m][n][c] * r, uu = acc[ai][1][m][n][c] * r; v[4 * n + c] = g * sigm(g) * uu; }
;         u32x4 w; w.x = pk2(v[0], v[1]); w.y = pk2(v[2], v[3]); w.z = pk2(v[4], v[5]); w.w = pk2(v[6], v[7]);
.LBB0_771:
	s_lshl_b32 s8, s8, 8
	v_mov_b32 v150, 0
	v_xor_b32_e32 v173, 32, v171
	v_add3_u32 v190, s8, v151, v150
	v_lshlrev_b32_e32 v136, 4, v190
	v_lshl_add_u64 v[148:149], v[136:137], 2, v[138:139]
	global_load_dwordx4 v[174:177], v[148:149], off
	v_add_u32_e32 v148, 0x100, v136
	v_mov_b32_e32 v149, v137
	v_lshl_add_u64 v[148:149], v[148:149], 2, v[138:139]
	global_load_dwordx4 v[178:181], v[148:149], off
	v_add_u32_e32 v148, 0x200, v136
	v_mov_b32_e32 v149, v137
	v_lshl_add_u64 v[148:149], v[148:149], 2, v[138:139]
	global_load_dwordx4 v[182:185], v[148:149], off
	v_add_u32_e32 v148, 0x300, v136
	v_mov_b32_e32 v149, v137
	v_lshl_add_u64 v[148:149], v[148:149], 2, v[138:139]
	global_load_dwordx4 v[186:189], v[148:149], off
	v_add_u32_e32 v216, 0x800, v136
	v_mov_b32_e32 v217, v137
	v_lshl_add_u64 v[216:217], v[216:217], 2, v[138:139]
	global_load_dwordx4 v[200:203], v[216:217], off
	v_add_u32_e32 v216, 0x900, v136
	v_mov_b32_e32 v217, v137
	v_lshl_add_u64 v[216:217], v[216:217], 2, v[138:139]
	global_load_dwordx4 v[204:207], v[216:217], off
	v_add_u32_e32 v216, 0xa00, v136
	v_mov_b32_e32 v217, v137
	v_lshl_add_u64 v[216:217], v[216:217], 2, v[138:139]
	global_load_dwordx4 v[208:211], v[216:217], off
	v_add_u32_e32 v216, 0xb00, v136
	v_mov_b32_e32 v217, v137
	v_lshl_add_u64 v[216:217], v[216:217], 2, v[138:139]
	global_load_dwordx4 v[212:215], v[216:217], off
	v_and_b32_e32 v149, 64, v171
	v_xor_b32_e32 v148, 16, v171
	v_add_u32_e32 v191, 64, v149
	v_cmp_lt_i32_e32 vcc, v148, v191
	v_lshl_or_b32 v152, s9, 7, v154
	s_waitcnt vmcnt(0)
	v_mov_b32_e32 v149, v176
	v_cndmask_b32_e32 v148, v171, v148, vcc
	v_lshlrev_b32_e32 v172, 2, v148
	v_mov_b32_e32 v148, v175
	v_mov_b32_e32 v175, v177
	v_pk_add_f32 v[148:149], v[148:149], v[174:175]
	v_mov_b32_e32 v174, v179
	v_mov_b32_e32 v175, v180
	v_mov_b32_e32 v179, v181
	v_mov_b32_e32 v176, v183
	v_mov_b32_e32 v177, v184
	v_mov_b32_e32 v183, v185
	v_mov_b32_e32 v180, v187
	v_mov_b32_e32 v181, v188
	v_mov_b32_e32 v187, v189
	v_pk_add_f32 v[174:175], v[174:175], v[178:179]
	v_pk_add_f32 v[176:177], v[176:177], v[182:183]
	v_pk_add_f32 v[178:179], v[180:181], v[186:187]
	v_mov_b32_e32 v181, v148
	v_mov_b32_e32 v180, v174
	v_mov_b32_e32 v148, v175
	v_mov_b32_e32 v174, v178
	v_mov_b32_e32 v175, v176
	v_mov_b32_e32 v176, v179
	v_pk_add_f32 v[148:149], v[180:181], v[148:149]
	v_pk_add_f32 v[174:175], v[174:175], v[176:177]
	ds_bpermute_b32 v177, v172, v149
	ds_bpermute_b32 v176, v172, v148
	ds_bpermute_b32 v179, v172, v175
	ds_bpermute_b32 v178, v172, v174
	v_cmp_lt_i32_e32 vcc, v173, v191
	v_add_u32_e32 v182, v152, v150
	s_waitcnt lgkmcnt(2)
	v_pk_add_f32 v[176:177], v[148:149], v[176:177]
	v_cndmask_b32_e32 v173, v171, v173, vcc
	v_lshlrev_b32_e32 v173, 2, v173
	s_waitcnt lgkmcnt(0)
	v_pk_add_f32 v[174:175], v[174:175], v[178:179]
	ds_bpermute_b32 v179, v173, v177
	ds_bpermute_b32 v178, v173, v176
	ds_bpermute_b32 v181, v173, v175
	ds_bpermute_b32 v180, v173, v174
	v_mov_b64_e32 v[148:149], s[48:49]
	v_ashrrev_i32_e32 v183, 31, v182
	s_waitcnt lgkmcnt(2)
	v_pk_add_f32 v[176:177], v[176:177], v[178:179]
	s_waitcnt lgkmcnt(0)
	v_pk_add_f32 v[174:175], v[174:175], v[180:181]
	v_pk_fma_f32 v[176:177], v[176:177], s[20:21], v[148:149] op_sel_hi:[1,0,0]
	v_pk_fma_f32 v[174:175], v[174:175], s[20:21], v[148:149] op_sel_hi:[1,0,0]
	v_mul_f32_e32 v150, 0x4b800000, v177
	v_cmp_gt_f32_e32 vcc, s68, v177
	v_mul_f32_e32 v152, 0x4b800000, v176
	v_mul_f32_e32 v178, 0x4b800000, v175
	v_cndmask_b32_e32 v150, v177, v150, vcc
	v_mul_f32_e32 v179, 0x4b800000, v174
	v_cmp_gt_f32_e64 s[8:9], s68, v176
	v_cmp_gt_f32_e64 s[10:11], s68, v175
	v_cmp_gt_f32_e64 s[12:13], s68, v174
	v_rsq_f32_e32 v150, v150
	v_cndmask_b32_e64 v152, v176, v152, s[8:9]
	v_cndmask_b32_e64 v175, v175, v178, s[10:11]
	v_cndmask_b32_e64 v174, v174, v179, s[12:13]
	v_rsq_f32_e32 v152, v152
	v_rsq_f32_e32 v175, v175
	v_rsq_f32_e32 v177, v174
	v_mul_f32_e32 v174, 0x45800000, v150
	v_cndmask_b32_e32 v174, v150, v174, vcc
	v_mul_f32_e32 v176, 0x45800000, v152
	v_mul_f32_e32 v178, 0x45800000, v175
	v_mul_f32_e32 v179, 0x45800000, v177
	v_pk_mul_f32 v[124:125], v[124:125], v[174:175] op_sel_hi:[1,0]
	v_pk_mul_f32 v[126:127], v[126:127], v[174:175] op_sel_hi:[1,0]
	v_cndmask_b32_e64 v176, v152, v176, s[8:9]
	v_cndmask_b32_e64 v152, v175, v178, s[10:11]
	v_cndmask_b32_e64 v150, v177, v179, s[12:13]
	v_pk_mul_f32 v[120:121], v[120:121], v[174:175] op_sel_hi:[1,0]
	v_pk_mul_f32 v[122:123], v[122:123], v[174:175] op_sel_hi:[1,0]
	v_pk_mul_f32 v[116:117], v[116:117], v[174:175] op_sel_hi:[1,0]
	v_mul_f32_e32 v175, 0xbfb8aa3b, v124
	v_mul_f32_e32 v178, 0xbfb8aa3b, v126
	v_mul_f32_e32 v179, 0xbfb8aa3b, v127
	v_exp_f32_e32 v175, v175
	v_exp_f32_e32 v178, v178
	v_exp_f32_e32 v179, v179
	v_mul_f32_e32 v177, 0xbfb8aa3b, v125
	v_mul_f32_e32 v184, 0xbfb8aa3b, v116
	v_exp_f32_e32 v177, v177
	v_add_f32_e32 v175, 1.0, v175
	v_add_f32_e32 v180, 1.0, v178
	v_add_f32_e32 v181, 1.0, v179
	v_rcp_f32_e32 v178, v175
	v_rcp_f32_e32 v180, v180
	v_rcp_f32_e32 v181, v181
	v_exp_f32_e32 v175, v184
	v_add_f32_e32 v177, 1.0, v177
	v_mul_f32_e32 v185, 0xbfb8aa3b, v117
	v_rcp_f32_e32 v179, v177
	v_pk_mul_f32 v[126:127], v[126:127], v[180:181]
	v_pk_mul_f32 v[118:119], v[118:119], v[174:175] op_sel_hi:[1,0]
	v_exp_f32_e32 v177, v185
	v_pk_mul_f32 v[122:123], v[122:123], v[126:127]
	v_mul_f32_e32 v126, 0xbfb8aa3b, v118
	v_mul_f32_e32 v127, 0xbfb8aa3b, v119
	v_exp_f32_e32 v126, v126
	v_exp_f32_e32 v127, v127
	v_pk_mul_f32 v[124:125], v[124:125], v[178:179]
	v_pk_mul_f32 v[112:113], v[112:113], v[174:175] op_sel_hi:[1,0]
	v_pk_mul_f32 v[120:121], v[120:121], v[124:125]
	v_add_f32_e32 v124, 1.0, v175
; __device__ __forceinline__ unsigned pk2(float lo, float hi) { f32x2_t v = {lo, hi}; bf16x2_t b = __builtin_convertvector(v, bf16x2_t); return __builtin_bit_cast(unsigned, b); }
; __device__ __forceinline__ float sigm(float x) { return frcp(1.f + fexp2(-LOG2E * x)); }
;   __device__ __forceinline__ void operator()(const pg8::f32x4 (&acc)[2][2][4][2], const pg8::Unit& u, int wr, int wc, int fr, int fq) const {
;     ...
;       for (int m = 0; m < 4; ++m) {
;         const float r = rs[m]; float v[8];
; #pragma unroll
;         for (int n = 0; n < 2; ++n)
; #pragma unroll
;           for (int c = 0; c < 4; ++c) { const float g = acc[ai][0][m][n][c] * r, uu = acc[ai][1][m][n][c] * r; v[4 * n + c] = g * sigm(g) * uu; }
;         u32x4 w; w.x = pk2(v[0], v[1]); w.y = pk2(v[2], v[3]); w.z = pk2(v[4], v[5]); w.w = pk2(v[6], v[7]);
;         *(u32x4*)(hbuf + (unsigned)(row0 + ai * 128 + m * 16) * DFF + col0) = w;
;       }
	v_add_f32_e32 v125, 1.0, v177
	v_rcp_f32_e32 v124, v124
	v_rcp_f32_e32 v125, v125
	v_add_f32_e32 v126, 1.0, v126
	v_add_f32_e32 v127, 1.0, v127
	v_rcp_f32_e32 v126, v126
	v_rcp_f32_e32 v127, v127
	v_pk_mul_f32 v[116:117], v[116:117], v[124:125]
	v_pk_mul_f32 v[114:115], v[114:115], v[174:175] op_sel_hi:[1,0]
	v_pk_mul_f32 v[112:113], v[112:113], v[116:117]
	v_pk_mul_f32 v[116:117], v[118:119], v[126:127]
	v_cvt_pk_bf16_f32 v118, v112, v113
	v_pk_mul_f32 v[114:115], v[114:115], v[116:117]
	v_cvt_pk_bf16_f32 v116, v120, v121
	v_cvt_pk_bf16_f32 v119, v114, v115
	v_mul_lo_u32 v114, v190, s69
	v_mov_b32_e32 v115, v137
	v_lshl_add_u64 v[120:121], v[114:115], 1, s[38:39]
	v_lshlrev_b64 v[112:113], 1, v[182:183]
	v_pk_mul_f32 v[108:109], v[108:109], v[176:177] op_sel_hi:[1,0]
	v_cvt_pk_bf16_f32 v117, v122, v123
	v_lshl_add_u64 v[120:121], v[120:121], 0, v[112:113]
	v_mul_f32_e32 v115, 0xbfb8aa3b, v108
	v_exp_f32_e32 v115, v115
	global_store_dwordx4 v[120:121], v[116:119], off
	v_pk_mul_f32 v[110:111], v[110:111], v[176:177] op_sel_hi:[1,0]
	v_pk_mul_f32 v[100:101], v[100:101], v[176:177] op_sel_hi:[1,0]
	v_mul_f32_e32 v116, 0xbfb8aa3b, v109
	v_exp_f32_e32 v117, v116
	v_add_f32_e32 v115, 1.0, v115
	v_rcp_f32_e32 v116, v115
	v_pk_mul_f32 v[104:105], v[104:105], v[176:177] op_sel_hi:[1,0]
	v_add_f32_e32 v115, 1.0, v117
	v_mul_f32_e32 v117, 0xbfb8aa3b, v110
	v_exp_f32_e32 v118, v117
	v_mul_f32_e32 v117, 0xbfb8aa3b, v111
	v_exp_f32_e32 v119, v117
	v_rcp_f32_e32 v117, v115
	v_add_f32_e32 v115, 1.0, v118
	v_rcp_f32_e32 v118, v115
	v_add_f32_e32 v115, 1.0, v119
	v_rcp_f32_e32 v119, v115
	v_pk_mul_f32 v[108:109], v[108:109], v[116:117]
	v_pk_mul_f32 v[102:103], v[102:103], v[176:177] op_sel_hi:[1,0]
	v_pk_mul_f32 v[100:101], v[100:101], v[108:109]
	v_pk_mul_f32 v[108:109], v[110:111], v[118:119]
	v_mul_f32_e32 v110, 0xbfb8aa3b, v104
	v_exp_f32_e32 v110, v110
	v_pk_mul_f32 v[102:103], v[102:103], v[108:109]
	v_mul_f32_e32 v108, 0xbfb8aa3b, v105
	v_pk_mul_f32 v[106:107], v[106:107], v[176:177] op_sel_hi:[1,0]
	v_exp_f32_e32 v109, v108
	v_add_f32_e32 v108, 1.0, v110
	v_mul_f32_e32 v110, 0xbfb8aa3b, v106
	v_mul_f32_e32 v111, 0xbfb8aa3b, v107
	v_exp_f32_e32 v110, v110
	v_exp_f32_e32 v111, v111
	v_add_f32_e32 v109, 1.0, v109
	v_rcp_f32_e32 v108, v108
	v_rcp_f32_e32 v109, v109
	v_add_f32_e32 v110, 1.0, v110
	v_add_f32_e32 v111, 1.0, v111
	v_rcp_f32_e32 v110, v110
	v_rcp_f32_e32 v111, v111
	v_pk_mul_f32 v[96:97], v[96:97], v[176:177] op_sel_hi:[1,0]
	v_pk_mul_f32 v[104:105], v[104:105], v[108:109]
	v_pk_mul_f32 v[92:93], v[92:93], v[152:153] op_sel_hi:[1,0]
	v_pk_mul_f32 v[104:105], v[96:97], v[104:105]
	v_pk_mul_f32 v[96:97], v[98:99], v[176:177] op_sel_hi:[1,0]
	v_pk_mul_f32 v[98:99], v[106:107], v[110:111]
	v_pk_mul_f32 v[94:95], v[94:95], v[152:153] op_sel_hi:[1,0]
	v_pk_mul_f32 v[106:107], v[96:97], v[98:99]
	v_cvt_pk_bf16_f32 v96, v100, v101
	v_add_u32_e32 v100, 0xb000, v114
	v_mov_b32_e32 v101, v137
	v_lshl_add_u64 v[100:101], v[100:101], 1, s[38:39]
	v_cvt_pk_bf16_f32 v97, v102, v103
	v_cvt_pk_bf16_f32 v98, v104, v105
	v_cvt_pk_bf16_f32 v99, v106, v107
	v_lshl_add_u64 v[100:101], v[100:101], 0, v[112:113]
	v_mul_f32_e32 v102, 0xbfb8aa3b, v92
	global_store_dwordx4 v[100:101], v[96:99], off
	v_exp_f32_e32 v102, v102
	v_pk_mul_f32 v[84:85], v[84:85], v[152:153] op_sel_hi:[1,0]
	v_mul_f32_e32 v96, 0xbfb8aa3b, v93
	v_exp_f32_e32 v97, v96
	v_mul_f32_e32 v98, 0xbfb8aa3b, v94
	v_mul_f32_e32 v99, 0xbfb8aa3b, v95
	v_exp_f32_e32 v98, v98
	v_exp_f32_e32 v99, v99
	v_add_f32_e32 v96, 1.0, v102
	v_add_f32_e32 v97, 1.0, v97
	v_rcp_f32_e32 v96, v96
	v_rcp_f32_e32 v97, v97
	v_add_f32_e32 v98, 1.0, v98
	v_add_f32_e32 v99, 1.0, v99
	v_rcp_f32_e32 v98, v98
	v_rcp_f32_e32 v99, v99
	v_pk_mul_f32 v[92:93], v[92:93], v[96:97]
	v_pk_mul_f32 v[88:89], v[88:89], v[152:153] op_sel_hi:[1,0]
	v_pk_mul_f32 v[84:85], v[84:85], v[92:93]
	v_pk_mul_f32 v[92:93], v[94:95], v[98:99]
	v_mul_f32_e32 v94, 0xbfb8aa3b, v88
	v_exp_f32_e32 v94, v94
	v_pk_mul_f32 v[86:87], v[86:87], v[152:153] op_sel_hi:[1,0]
	v_pk_mul_f32 v[90:91], v[90:91], v[152:153] op_sel_hi:[1,0]
	v_pk_mul_f32 v[86:87], v[86:87], v[92:93]
	v_mul_f32_e32 v92, 0xbfb8aa3b, v89
	v_exp_f32_e32 v93, v92
	v_add_f32_e32 v92, 1.0, v94
	v_mul_f32_e32 v94, 0xbfb8aa3b, v90
	v_mul_f32_e32 v95, 0xbfb8aa3b, v91
	v_exp_f32_e32 v94, v94
	v_exp_f32_e32 v95, v95
	v_add_f32_e32 v93, 1.0, v93
	v_rcp_f32_e32 v92, v92
	v_rcp_f32_e32 v93, v93
	v_add_f32_e32 v94, 1.0, v94
	v_add_f32_e32 v95, 1.0, v95
	v_rcp_f32_e32 v94, v94
	v_rcp_f32_e32 v95, v95
	v_pk_mul_f32 v[80:81], v[80:81], v[152:153] op_sel_hi:[1,0]
	v_pk_mul_f32 v[88:89], v[88:89], v[92:93]
	v_pk_mul_f32 v[76:77], v[76:77], v[150:151] op_sel_hi:[1,0]
	v_pk_mul_f32 v[88:89], v[80:81], v[88:89]
	v_pk_mul_f32 v[80:81], v[82:83], v[152:153] op_sel_hi:[1,0]
	v_pk_mul_f32 v[82:83], v[90:91], v[94:95]
	v_pk_mul_f32 v[78:79], v[78:79], v[150:151] op_sel_hi:[1,0]
	v_pk_mul_f32 v[90:91], v[80:81], v[82:83]
	v_cvt_pk_bf16_f32 v80, v84, v85
	v_add_u32_e32 v84, 0x16000, v114
	v_mov_b32_e32 v85, v137
	v_lshl_add_u64 v[84:85], v[84:85], 1, s[38:39]
	v_cvt_pk_bf16_f32 v81, v86, v87
	v_cvt_pk_bf16_f32 v82, v88, v89
	v_cvt_pk_bf16_f32 v83, v90, v91
	v_lshl_add_u64 v[84:85], v[84:85], 0, v[112:113]
	v_mul_f32_e32 v86, 0xbfb8aa3b, v76
	global_store_dwordx4 v[84:85], v[80:83], off
	v_exp_f32_e32 v86, v86
	v_pk_mul_f32 v[68:69], v[68:69], v[150:151] op_sel_hi:[1,0]
	v_mul_f32_e32 v80, 0xbfb8aa3b, v77
	v_exp_f32_e32 v81, v80
	v_mul_f32_e32 v82, 0xbfb8aa3b, v78
	v_mul_f32_e32 v83, 0xbfb8aa3b, v79
	v_exp_f32_e32 v82, v82
	v_exp_f32_e32 v83, v83
	v_add_f32_e32 v80, 1.0, v86
	v_add_f32_e32 v81, 1.0, v81
; __device__ __forceinline__ unsigned pk2(float lo, float hi) { f32x2_t v = {lo, hi}; bf16x2_t b = __builtin_convertvector(v, bf16x2_t); return __builtin_bit_cast(unsigned, b); }
; __device__ __forceinline__ float sigm(float x) { return frcp(1.f + fexp2(-LOG2E * x)); }
;   __device__ __forceinline__ void operator()(const pg8::f32x4 (&acc)[2][2][4][2], const pg8::Unit& u, int wr, int wc, int fr, int fq) const {
;     ...
;       for (int m = 0; m < 4; ++m) { const f32x4 a = *(const f32x4*)(ssq + (unsigned)(row0 + ai * 128 + m * 16) * 16 + 4 * fq); rs[m] = (a[0] + a[1]) + (a[2] + a[3]); }
; #pragma unroll
;       for (int m = 0; m < 4; ++m) { float v = rs[m]; v += __shfl_xor(v, 16); v += __shfl_xor(v, 32); rs[m] = rsqrtf(v * (1.f / 1024.f) + EPS); }
; #pragma unroll
;       for (int m = 0; m < 4; ++m) {
;         const float r = rs[m]; float v[8];
; #pragma unroll
;         for (int n = 0; n < 2; ++n)
; #pragma unroll
;           for (int c = 0; c < 4; ++c) { const float g = acc[ai][0][m][n][c] * r, uu = acc[ai][1][m][n][c] * r; v[4 * n + c] = g * sigm(g) * uu; }
;         u32x4 w; w.x = pk2(v[0], v[1]); w.y = pk2(v[2], v[3]); w.z = pk2(v[4], v[5]); w.w = pk2(v[6], v[7]);
;         *(u32x4*)(hbuf + (unsigned)(row0 + ai * 128 + m * 16) * DFF + col0) = w;
;       }
	v_rcp_f32_e32 v80, v80
	v_rcp_f32_e32 v81, v81
	v_add_f32_e32 v82, 1.0, v82
	v_add_f32_e32 v83, 1.0, v83
	v_rcp_f32_e32 v82, v82
	v_rcp_f32_e32 v83, v83
	v_pk_mul_f32 v[76:77], v[76:77], v[80:81]
	v_pk_mul_f32 v[72:73], v[72:73], v[150:151] op_sel_hi:[1,0]
	v_pk_mul_f32 v[68:69], v[68:69], v[76:77]
	v_pk_mul_f32 v[76:77], v[78:79], v[82:83]
	v_mul_f32_e32 v78, 0xbfb8aa3b, v72
	v_exp_f32_e32 v78, v78
	v_pk_mul_f32 v[70:71], v[70:71], v[150:151] op_sel_hi:[1,0]
	v_pk_mul_f32 v[74:75], v[74:75], v[150:151] op_sel_hi:[1,0]
	v_pk_mul_f32 v[70:71], v[70:71], v[76:77]
	v_mul_f32_e32 v76, 0xbfb8aa3b, v73
	v_exp_f32_e32 v77, v76
	v_add_f32_e32 v76, 1.0, v78
	v_mul_f32_e32 v78, 0xbfb8aa3b, v74
	v_mul_f32_e32 v79, 0xbfb8aa3b, v75
	v_exp_f32_e32 v78, v78
	v_exp_f32_e32 v79, v79
	v_add_f32_e32 v77, 1.0, v77
	v_rcp_f32_e32 v76, v76
	v_rcp_f32_e32 v77, v77
	v_add_f32_e32 v78, 1.0, v78
	v_add_f32_e32 v79, 1.0, v79
	v_rcp_f32_e32 v78, v78
	v_rcp_f32_e32 v79, v79
	v_pk_mul_f32 v[64:65], v[64:65], v[150:151] op_sel_hi:[1,0]
	v_pk_mul_f32 v[72:73], v[72:73], v[76:77]
	s_nop 0
	v_pk_mul_f32 v[72:73], v[64:65], v[72:73]
	v_pk_mul_f32 v[64:65], v[66:67], v[150:151] op_sel_hi:[1,0]
	v_pk_mul_f32 v[66:67], v[74:75], v[78:79]
	s_nop 0
	v_pk_mul_f32 v[74:75], v[64:65], v[66:67]
	v_cvt_pk_bf16_f32 v64, v68, v69
	v_add_u32_e32 v68, 0x21000, v114
	v_mov_b32_e32 v69, v137
	v_lshl_add_u64 v[68:69], v[68:69], 1, s[38:39]
	v_cvt_pk_bf16_f32 v65, v70, v71
	v_cvt_pk_bf16_f32 v66, v72, v73
	v_cvt_pk_bf16_f32 v67, v74, v75
	v_lshl_add_u64 v[68:69], v[68:69], 0, v[112:113]
	global_store_dwordx4 v[68:69], v[64:67], off
	v_add_u32_e32 v136, 0x58000, v114
	v_mov_b64_e32 v[72:73], v[208:209]
	v_mov_b64_e32 v[74:75], v[210:211]
	v_mov_b64_e32 v[76:77], v[212:213]
	v_mov_b64_e32 v[78:79], v[214:215]
	v_mov_b64_e32 v[64:65], v[200:201]
	v_mov_b64_e32 v[66:67], v[202:203]
	v_mov_b64_e32 v[68:69], v[204:205]
	v_mov_b64_e32 v[70:71], v[206:207]
	v_mov_b32_e32 v80, v65
	v_mov_b32_e32 v81, v66
	v_mov_b32_e32 v65, v67
	v_mov_b32_e32 v66, v69
	v_mov_b32_e32 v67, v70
	v_mov_b32_e32 v69, v71
	v_pk_add_f32 v[64:65], v[80:81], v[64:65]
	v_pk_add_f32 v[66:67], v[66:67], v[68:69]
	v_mov_b32_e32 v69, v64
	v_mov_b32_e32 v68, v66
	v_mov_b32_e32 v64, v67
	v_pk_add_f32 v[64:65], v[68:69], v[64:65]
	ds_bpermute_b32 v67, v172, v65
	ds_bpermute_b32 v66, v172, v64
	v_mov_b32_e32 v68, v73
	v_mov_b32_e32 v69, v74
	v_mov_b32_e32 v73, v75
	v_mov_b32_e32 v70, v77
	s_waitcnt lgkmcnt(0)
	v_pk_add_f32 v[64:65], v[64:65], v[66:67]
	ds_bpermute_b32 v67, v173, v65
	ds_bpermute_b32 v66, v173, v64
	v_mov_b32_e32 v71, v78
	v_mov_b32_e32 v77, v79
	v_pk_add_f32 v[68:69], v[68:69], v[72:73]
	v_pk_add_f32 v[70:71], v[70:71], v[76:77]
	s_waitcnt lgkmcnt(0)
	v_pk_add_f32 v[64:65], v[64:65], v[66:67]
	v_mov_b32_e32 v67, v68
	v_pk_fma_f32 v[64:65], v[64:65], s[20:21], v[148:149] op_sel_hi:[1,0,0]
	v_mov_b32_e32 v68, v71
	v_mul_f32_e32 v66, 0x4b800000, v65
	v_cmp_gt_f32_e32 vcc, s68, v65
	v_cmp_gt_f32_e64 s[8:9], s68, v64
	s_nop 0
	v_cndmask_b32_e32 v65, v65, v66, vcc
	v_mov_b32_e32 v66, v70
	v_pk_add_f32 v[66:67], v[66:67], v[68:69]
	ds_bpermute_b32 v69, v172, v67
	ds_bpermute_b32 v68, v172, v66
	v_rsq_f32_e32 v72, v65
	v_mul_f32_e32 v65, 0x4b800000, v64
	v_cndmask_b32_e64 v64, v64, v65, s[8:9]
	v_rsq_f32_e32 v70, v64
	s_waitcnt lgkmcnt(0)
	v_pk_add_f32 v[64:65], v[66:67], v[68:69]
	ds_bpermute_b32 v67, v173, v65
	ds_bpermute_b32 v66, v173, v64
	v_mul_f32_e32 v68, 0x45800000, v72
	v_cndmask_b32_e32 v68, v72, v68, vcc
	v_mul_f32_e32 v69, 0x45800000, v70
	v_pk_mul_f32 v[62:63], v[62:63], v[68:69] op_sel_hi:[1,0]
	s_waitcnt lgkmcnt(0)
	v_pk_add_f32 v[64:65], v[64:65], v[66:67]
	v_pk_mul_f32 v[56:57], v[56:57], v[68:69] op_sel_hi:[1,0]
	v_pk_fma_f32 v[64:65], v[64:65], s[20:21], v[148:149] op_sel_hi:[1,0,0]
	v_pk_mul_f32 v[54:55], v[54:55], v[68:69] op_sel_hi:[1,0]
	v_mul_f32_e32 v66, 0x4b800000, v65
	v_cmp_gt_f32_e32 vcc, s68, v65
	v_cmp_gt_f32_e64 s[10:11], s68, v64
	v_pk_mul_f32 v[58:59], v[58:59], v[68:69] op_sel_hi:[1,0]
	v_cndmask_b32_e32 v65, v65, v66, vcc
	v_mul_f32_e32 v66, 0x4b800000, v64
	v_rsq_f32_e32 v65, v65
	v_cndmask_b32_e64 v64, v64, v66, s[10:11]
	v_rsq_f32_e32 v67, v64
	v_cndmask_b32_e64 v66, v70, v69, s[8:9]
	v_mul_f32_e32 v64, 0x45800000, v65
	v_pk_mul_f32 v[70:71], v[60:61], v[68:69] op_sel_hi:[1,0]
	v_cndmask_b32_e32 v64, v65, v64, vcc
	v_mul_f32_e32 v65, 0x45800000, v67
	v_mul_f32_e32 v60, 0xbfb8aa3b, v70
	v_exp_f32_e32 v61, v60
	v_cndmask_b32_e64 v60, v67, v65, s[10:11]
	v_mul_f32_e32 v65, 0xbfb8aa3b, v71
	v_exp_f32_e32 v65, v65
	v_add_f32_e32 v61, 1.0, v61
	v_rcp_f32_e32 v72, v61
	v_mul_f32_e32 v67, 0xbfb8aa3b, v63
	v_add_f32_e32 v61, 1.0, v65
	v_mul_f32_e32 v65, 0xbfb8aa3b, v62
	v_exp_f32_e32 v65, v65
	v_exp_f32_e32 v67, v67
	v_rcp_f32_e32 v73, v61
	v_pk_mul_f32 v[52:53], v[52:53], v[68:69] op_sel_hi:[1,0]
	v_add_f32_e32 v61, 1.0, v65
	v_rcp_f32_e32 v74, v61
	v_add_f32_e32 v61, 1.0, v67
	v_rcp_f32_e32 v75, v61
	v_mul_f32_e32 v61, 0xbfb8aa3b, v56
	v_exp_f32_e32 v61, v61
	v_pk_mul_f32 v[70:71], v[70:71], v[72:73]
	v_pk_mul_f32 v[62:63], v[62:63], v[74:75]
	v_pk_mul_f32 v[52:53], v[52:53], v[70:71]
	v_pk_mul_f32 v[54:55], v[54:55], v[62:63]
	v_mul_f32_e32 v62, 0xbfb8aa3b, v57
	v_exp_f32_e32 v63, v62
	v_add_f32_e32 v61, 1.0, v61
	v_rcp_f32_e32 v62, v61
	v_pk_mul_f32 v[48:49], v[48:49], v[68:69] op_sel_hi:[1,0]
	v_add_f32_e32 v61, 1.0, v63
	v_mul_f32_e32 v63, 0xbfb8aa3b, v58
	v_exp_f32_e32 v65, v63
	v_mul_f32_e32 v63, 0xbfb8aa3b, v59
	v_exp_f32_e32 v67, v63
	v_rcp_f32_e32 v63, v61
	v_add_f32_e32 v61, 1.0, v65
	v_rcp_f32_e32 v70, v61
	v_add_f32_e32 v61, 1.0, v67
	v_rcp_f32_e32 v71, v61
; __device__ __forceinline__ unsigned pk2(float lo, float hi) { f32x2_t v = {lo, hi}; bf16x2_t b = __builtin_convertvector(v, bf16x2_t); return __builtin_bit_cast(unsigned, b); }
; __device__ __forceinline__ float sigm(float x) { return frcp(1.f + fexp2(-LOG2E * x)); }
; #define PG8_BAR __builtin_amdgcn_s_barrier()
; template <class Epi, class Sched, bool ALIGN_EPI = false, bool SP2 = false, bool F16 = false, bool TOKPERM = false>
; __device__ __forceinline__ void gemm_phase(PG8_LAS unsigned char* lds, const Gemm g, const Sched& S, const Epi& E, int wv) {
;     ...
;         if constexpr (ALIGN_EPI) { if (wr == 0) PG8_BAR; }
;         if constexpr (!Epi::AFTER_DRAIN) { E(acc, cur, wr, wc, fr, fq); S.done(cur); }
;         if (!has_next) break;
; #pragma unroll
;         for (int a = 0; a < 2; ++a)
; #pragma unroll
;             for (int b = 0; b < 2; ++b)
; #pragma unroll
;                 for (int m = 0; m < 4; ++m)
; #pragma unroll
;                     for (int n = 0; n < 2; ++n) acc[a][b][m][n] = (f32x4){0.f, 0.f, 0.f, 0.f};
;         cur = nxt; cA = nA; cB = nB; ++ui;
;         if constexpr (ALIGN_EPI) { if (wr == 1) PG8_BAR; }
;   __device__ __forceinline__ void operator()(const pg8::f32x4 (&acc)[2][2][4][2], const pg8::Unit& u, int wr, int wc, int fr, int fq) const {
;     ...
;       for (int m = 0; m < 4; ++m) {
;         const float r = rs[m]; float v[8];
; #pragma unroll
;         for (int n = 0; n < 2; ++n)
; #pragma unroll
;           for (int c = 0; c < 4; ++c) { const float g = acc[ai][0][m][n][c] * r, uu = acc[ai][1][m][n][c] * r; v[4 * n + c] = g * sigm(g) * uu; }
;         u32x4 w; w.x = pk2(v[0], v[1]); w.y = pk2(v[2], v[3]); w.z = pk2(v[4], v[5]); w.w = pk2(v[6], v[7]);
;         *(u32x4*)(hbuf + (unsigned)(row0 + ai * 128 + m * 16) * DFF + col0) = w;
;       }
	v_pk_mul_f32 v[56:57], v[56:57], v[62:63]
	v_pk_mul_f32 v[44:45], v[44:45], v[66:67] op_sel_hi:[1,0]
	v_pk_mul_f32 v[56:57], v[48:49], v[56:57]
	v_pk_mul_f32 v[48:49], v[50:51], v[68:69] op_sel_hi:[1,0]
	v_pk_mul_f32 v[50:51], v[58:59], v[70:71]
	v_pk_mul_f32 v[46:47], v[46:47], v[66:67] op_sel_hi:[1,0]
	v_pk_mul_f32 v[58:59], v[48:49], v[50:51]
	v_cvt_pk_bf16_f32 v48, v52, v53
	v_lshl_add_u64 v[52:53], v[136:137], 1, s[38:39]
	v_cvt_pk_bf16_f32 v49, v54, v55
	v_cvt_pk_bf16_f32 v50, v56, v57
	v_cvt_pk_bf16_f32 v51, v58, v59
	v_lshl_add_u64 v[52:53], v[52:53], 0, v[112:113]
	v_mul_f32_e32 v54, 0xbfb8aa3b, v44
	global_store_dwordx4 v[52:53], v[48:51], off
	v_exp_f32_e32 v54, v54
	v_pk_mul_f32 v[36:37], v[36:37], v[66:67] op_sel_hi:[1,0]
	v_mul_f32_e32 v48, 0xbfb8aa3b, v45
	v_exp_f32_e32 v49, v48
	v_mul_f32_e32 v50, 0xbfb8aa3b, v46
	v_mul_f32_e32 v51, 0xbfb8aa3b, v47
	v_exp_f32_e32 v50, v50
	v_exp_f32_e32 v51, v51
	v_add_f32_e32 v48, 1.0, v54
	v_add_f32_e32 v49, 1.0, v49
	v_rcp_f32_e32 v48, v48
	v_rcp_f32_e32 v49, v49
	v_add_f32_e32 v50, 1.0, v50
	v_add_f32_e32 v51, 1.0, v51
	v_rcp_f32_e32 v50, v50
	v_rcp_f32_e32 v51, v51
	v_pk_mul_f32 v[44:45], v[44:45], v[48:49]
	v_pk_mul_f32 v[40:41], v[40:41], v[66:67] op_sel_hi:[1,0]
	v_pk_mul_f32 v[36:37], v[36:37], v[44:45]
	v_pk_mul_f32 v[44:45], v[46:47], v[50:51]
	v_mul_f32_e32 v46, 0xbfb8aa3b, v40
	v_exp_f32_e32 v46, v46
	v_pk_mul_f32 v[38:39], v[38:39], v[66:67] op_sel_hi:[1,0]
	v_pk_mul_f32 v[42:43], v[42:43], v[66:67] op_sel_hi:[1,0]
	v_pk_mul_f32 v[38:39], v[38:39], v[44:45]
	v_mul_f32_e32 v44, 0xbfb8aa3b, v41
	v_exp_f32_e32 v45, v44
	v_add_f32_e32 v44, 1.0, v46
	v_mul_f32_e32 v46, 0xbfb8aa3b, v42
	v_mul_f32_e32 v47, 0xbfb8aa3b, v43
	v_exp_f32_e32 v46, v46
	v_exp_f32_e32 v47, v47
	v_add_f32_e32 v45, 1.0, v45
	v_rcp_f32_e32 v44, v44
	v_rcp_f32_e32 v45, v45
	v_add_f32_e32 v46, 1.0, v46
	v_add_f32_e32 v47, 1.0, v47
	v_rcp_f32_e32 v46, v46
	v_rcp_f32_e32 v47, v47
	v_pk_mul_f32 v[32:33], v[32:33], v[66:67] op_sel_hi:[1,0]
	v_pk_mul_f32 v[40:41], v[40:41], v[44:45]
	v_add_u32_e32 v136, 0x63000, v114
	v_pk_mul_f32 v[40:41], v[32:33], v[40:41]
	v_pk_mul_f32 v[32:33], v[34:35], v[66:67] op_sel_hi:[1,0]
	v_pk_mul_f32 v[34:35], v[42:43], v[46:47]
	v_pk_mul_f32 v[28:29], v[28:29], v[64:65] op_sel_hi:[1,0]
	v_pk_mul_f32 v[42:43], v[32:33], v[34:35]
	v_cvt_pk_bf16_f32 v32, v36, v37
	v_lshl_add_u64 v[36:37], v[136:137], 1, s[38:39]
	v_cvt_pk_bf16_f32 v33, v38, v39
	v_cvt_pk_bf16_f32 v34, v40, v41
	v_cvt_pk_bf16_f32 v35, v42, v43
	v_lshl_add_u64 v[36:37], v[36:37], 0, v[112:113]
	v_mul_f32_e32 v38, 0xbfb8aa3b, v28
	global_store_dwordx4 v[36:37], v[32:35], off
	v_pk_mul_f32 v[30:31], v[30:31], v[64:65] op_sel_hi:[1,0]
	v_exp_f32_e32 v38, v38
	v_mul_f32_e32 v32, 0xbfb8aa3b, v29
	v_exp_f32_e32 v33, v32
	v_mul_f32_e32 v34, 0xbfb8aa3b, v30
	v_mul_f32_e32 v35, 0xbfb8aa3b, v31
	v_exp_f32_e32 v34, v34
	v_exp_f32_e32 v35, v35
	v_add_f32_e32 v32, 1.0, v38
	v_add_f32_e32 v33, 1.0, v33
	v_rcp_f32_e32 v32, v32
	v_rcp_f32_e32 v33, v33
	v_add_f32_e32 v34, 1.0, v34
	v_add_f32_e32 v35, 1.0, v35
	v_rcp_f32_e32 v34, v34
	v_rcp_f32_e32 v35, v35
	v_pk_mul_f32 v[20:21], v[20:21], v[64:65] op_sel_hi:[1,0]
	v_pk_mul_f32 v[28:29], v[28:29], v[32:33]
	v_pk_mul_f32 v[24:25], v[24:25], v[64:65] op_sel_hi:[1,0]
	v_pk_mul_f32 v[20:21], v[20:21], v[28:29]
	v_pk_mul_f32 v[28:29], v[30:31], v[34:35]
	v_mul_f32_e32 v30, 0xbfb8aa3b, v24
	v_exp_f32_e32 v30, v30
	v_pk_mul_f32 v[22:23], v[22:23], v[64:65] op_sel_hi:[1,0]
	v_pk_mul_f32 v[26:27], v[26:27], v[64:65] op_sel_hi:[1,0]
	v_pk_mul_f32 v[22:23], v[22:23], v[28:29]
	v_mul_f32_e32 v28, 0xbfb8aa3b, v25
	v_exp_f32_e32 v29, v28
	v_add_f32_e32 v28, 1.0, v30
	v_mul_f32_e32 v30, 0xbfb8aa3b, v26
	v_mul_f32_e32 v31, 0xbfb8aa3b, v27
	v_exp_f32_e32 v30, v30
	v_exp_f32_e32 v31, v31
	v_add_f32_e32 v29, 1.0, v29
	v_rcp_f32_e32 v28, v28
	v_rcp_f32_e32 v29, v29
	v_add_f32_e32 v30, 1.0, v30
	v_add_f32_e32 v31, 1.0, v31
	v_rcp_f32_e32 v30, v30
	v_rcp_f32_e32 v31, v31
	v_pk_mul_f32 v[16:17], v[16:17], v[64:65] op_sel_hi:[1,0]
	v_pk_mul_f32 v[24:25], v[24:25], v[28:29]
	v_add_u32_e32 v136, 0x6e000, v114
	v_pk_mul_f32 v[24:25], v[16:17], v[24:25]
	v_pk_mul_f32 v[16:17], v[18:19], v[64:65] op_sel_hi:[1,0]
	v_pk_mul_f32 v[18:19], v[26:27], v[30:31]
	v_pk_mul_f32 v[12:13], v[12:13], v[60:61] op_sel_hi:[1,0]
	v_pk_mul_f32 v[26:27], v[16:17], v[18:19]
	v_cvt_pk_bf16_f32 v16, v20, v21
	v_lshl_add_u64 v[20:21], v[136:137], 1, s[38:39]
	v_cvt_pk_bf16_f32 v17, v22, v23
	v_cvt_pk_bf16_f32 v18, v24, v25
	v_cvt_pk_bf16_f32 v19, v26, v27
	v_lshl_add_u64 v[20:21], v[20:21], 0, v[112:113]
	v_mul_f32_e32 v22, 0xbfb8aa3b, v12
	global_store_dwordx4 v[20:21], v[16:19], off
	v_pk_mul_f32 v[14:15], v[14:15], v[60:61] op_sel_hi:[1,0]
	v_exp_f32_e32 v22, v22
	v_mul_f32_e32 v16, 0xbfb8aa3b, v13
	v_exp_f32_e32 v17, v16
	v_mul_f32_e32 v18, 0xbfb8aa3b, v14
	v_mul_f32_e32 v19, 0xbfb8aa3b, v15
	v_exp_f32_e32 v18, v18
	v_exp_f32_e32 v19, v19
	v_add_f32_e32 v16, 1.0, v22
	v_add_f32_e32 v17, 1.0, v17
	v_rcp_f32_e32 v16, v16
	v_rcp_f32_e32 v17, v17
	v_add_f32_e32 v18, 1.0, v18
	v_add_f32_e32 v19, 1.0, v19
	v_rcp_f32_e32 v18, v18
	v_rcp_f32_e32 v19, v19
	v_pk_mul_f32 v[4:5], v[4:5], v[60:61] op_sel_hi:[1,0]
	v_pk_mul_f32 v[12:13], v[12:13], v[16:17]
	v_pk_mul_f32 v[8:9], v[8:9], v[60:61] op_sel_hi:[1,0]
	v_pk_mul_f32 v[4:5], v[4:5], v[12:13]
	v_pk_mul_f32 v[12:13], v[14:15], v[18:19]
	v_mul_f32_e32 v14, 0xbfb8aa3b, v8
	v_exp_f32_e32 v14, v14
	v_pk_mul_f32 v[6:7], v[6:7], v[60:61] op_sel_hi:[1,0]
	v_pk_mul_f32 v[10:11], v[10:11], v[60:61] op_sel_hi:[1,0]
	v_pk_mul_f32 v[6:7], v[6:7], v[12:13]
	v_mul_f32_e32 v12, 0xbfb8aa3b, v9
	v_exp_f32_e32 v13, v12
	v_add_f32_e32 v12, 1.0, v14
	v_mul_f32_e32 v14, 0xbfb8aa3b, v10
	v_mul_f32_e32 v15, 0xbfb8aa3b, v11
	v_exp_f32_e32 v14, v14
	v_exp_f32_e32 v15, v15
	v_add_f32_e32 v13, 1.0, v13
	v_rcp_f32_e32 v12, v12
	v_rcp_f32_e32 v13, v13
	v_add_f32_e32 v14, 1.0, v14
	v_add_f32_e32 v15, 1.0, v15
	v_rcp_f32_e32 v14, v14
	v_rcp_f32_e32 v15, v15
	v_pk_mul_f32 v[0:1], v[0:1], v[60:61] op_sel_hi:[1,0]
	v_pk_mul_f32 v[8:9], v[8:9], v[12:13]
	v_add_u32_e32 v136, 0x79000, v114
	v_pk_mul_f32 v[8:9], v[0:1], v[8:9]
	v_pk_mul_f32 v[0:1], v[2:3], v[60:61] op_sel_hi:[1,0]
	v_pk_mul_f32 v[2:3], v[10:11], v[14:15]
	s_andn2_b64 vcc, exec, s[6:7]
	v_pk_mul_f32 v[10:11], v[0:1], v[2:3]
	v_cvt_pk_bf16_f32 v0, v4, v5
	v_lshl_add_u64 v[4:5], v[136:137], 1, s[38:39]
	v_cvt_pk_bf16_f32 v1, v6, v7
	v_cvt_pk_bf16_f32 v2, v8, v9
	v_cvt_pk_bf16_f32 v3, v10, v11
	v_lshl_add_u64 v[4:5], v[4:5], 0, v[112:113]
	global_store_dwordx4 v[4:5], v[0:3], off
	s_mov_b64 s[6:7], -1
	s_cbranch_vccnz .LBB0_764
	s_andn2_b64 vcc, exec, s[14:15]
	s_cbranch_vccnz .LBB0_763
	s_barrier
	s_branch .LBB0_763

; __device__ __forceinline__ unsigned pk2(float lo, float hi) { f32x2_t v = {lo, hi}; bf16x2_t b = __builtin_convertvector(v, bf16x2_t); return __builtin_bit_cast(unsigned, b); }
; __device__ __forceinline__ float sigm(float x) { return frcp(1.f + fexp2(-LOG2E * x)); }
;   __device__ __forceinline__ void operator()(const pg8::f32x4 (&acc)[2][2][4][2], const pg8::Unit& u, int wr, int wc, int fr, int fq) const {
;     int z; asm volatile("v_mov_b32 %0, 0" : "=v"(z));
;     const int row0 = u.pm * 256 + wr * 64 + fr + z, col0 = u.pn * 128 + wc * 32 + 8 * fq + z;
; #pragma unroll
;     for (int ai = 0; ai < 2; ++ai) {
;       float rs[4];
; #pragma unroll
;       for (int m = 0; m < 4; ++m) { const f32x4 a = *(const f32x4*)(ssq + (unsigned)(row0 + ai * 128 + m * 16) * 16 + 4 * fq); rs[m] = (a[0] + a[1]) + (a[2] + a[3]); }
; #pragma unroll
;       for (int m = 0; m < 4; ++m) { float v = rs[m]; v += __shfl_xor(v, 16); v += __shfl_xor(v, 32); rs[m] = rsqrtf(v * (1.f / 1024.f) + EPS); }
; #pragma unroll
;       for (int m = 0; m < 4; ++m) {
;         const float r = rs[m]; float v[8];
; #pragma unroll
;         for (int n = 0; n < 2; ++n)
; #pragma unroll
;           for (int c = 0; c < 4; ++c) { const float g = acc[ai][0][m][n][c] * r, uu = acc[ai][1][m][n][c] * r; v[4 * n + c] = g * sigm(g) * uu; }
;         u32x4 w; w.x = pk2(v[0], v[1]); w.y = pk2(v[2], v[3]); w.z = pk2(v[4], v[5]); w.w = pk2(v[6], v[7]);
.LBB0_953:
	s_lshl_b32 s8, s8, 8
	v_mov_b32 v150, 0
	v_xor_b32_e32 v173, 32, v171
	v_add3_u32 v190, s8, v151, v150
	v_lshlrev_b32_e32 v136, 4, v190
	v_lshl_add_u64 v[148:149], v[136:137], 2, v[138:139]
	global_load_dwordx4 v[174:177], v[148:149], off
	v_add_u32_e32 v148, 0x100, v136
	v_mov_b32_e32 v149, v137
	v_lshl_add_u64 v[148:149], v[148:149], 2, v[138:139]
	global_load_dwordx4 v[178:181], v[148:149], off
	v_add_u32_e32 v148, 0x200, v136
	v_mov_b32_e32 v149, v137
	v_lshl_add_u64 v[148:149], v[148:149], 2, v[138:139]
	global_load_dwordx4 v[182:185], v[148:149], off
	v_add_u32_e32 v148, 0x300, v136
	v_mov_b32_e32 v149, v137
	v_lshl_add_u64 v[148:149], v[148:149], 2, v[138:139]
	global_load_dwordx4 v[186:189], v[148:149], off
	v_add_u32_e32 v216, 0x800, v136
	v_mov_b32_e32 v217, v137
	v_lshl_add_u64 v[216:217], v[216:217], 2, v[138:139]
	global_load_dwordx4 v[200:203], v[216:217], off
	v_add_u32_e32 v216, 0x900, v136
	v_mov_b32_e32 v217, v137
	v_lshl_add_u64 v[216:217], v[216:217], 2, v[138:139]
	global_load_dwordx4 v[204:207], v[216:217], off
	v_add_u32_e32 v216, 0xa00, v136
	v_mov_b32_e32 v217, v137
	v_lshl_add_u64 v[216:217], v[216:217], 2, v[138:139]
	global_load_dwordx4 v[208:211], v[216:217], off
	v_add_u32_e32 v216, 0xb00, v136
	v_mov_b32_e32 v217, v137
	v_lshl_add_u64 v[216:217], v[216:217], 2, v[138:139]
	global_load_dwordx4 v[212:215], v[216:217], off
	v_and_b32_e32 v149, 64, v171
	v_xor_b32_e32 v148, 16, v171
	v_add_u32_e32 v191, 64, v149
	v_cmp_lt_i32_e32 vcc, v148, v191
	v_lshl_or_b32 v152, s9, 7, v154
	s_waitcnt vmcnt(0)
	v_mov_b32_e32 v149, v176
	v_cndmask_b32_e32 v148, v171, v148, vcc
	v_lshlrev_b32_e32 v172, 2, v148
	v_mov_b32_e32 v148, v175
	v_mov_b32_e32 v175, v177
	v_pk_add_f32 v[148:149], v[148:149], v[174:175]
	v_mov_b32_e32 v174, v179
	v_mov_b32_e32 v175, v180
	v_mov_b32_e32 v179, v181
	v_mov_b32_e32 v176, v183
	v_mov_b32_e32 v177, v184
	v_mov_b32_e32 v183, v185
	v_mov_b32_e32 v180, v187
	v_mov_b32_e32 v181, v188
	v_mov_b32_e32 v187, v189
	v_pk_add_f32 v[174:175], v[174:175], v[178:179]
	v_pk_add_f32 v[176:177], v[176:177], v[182:183]
	v_pk_add_f32 v[178:179], v[180:181], v[186:187]
	v_mov_b32_e32 v181, v148
	v_mov_b32_e32 v180, v174
	v_mov_b32_e32 v148, v175
	v_mov_b32_e32 v174, v178
	v_mov_b32_e32 v175, v176
	v_mov_b32_e32 v176, v179
	v_pk_add_f32 v[148:149], v[180:181], v[148:149]
	v_pk_add_f32 v[174:175], v[174:175], v[176:177]
	ds_bpermute_b32 v177, v172, v149
	ds_bpermute_b32 v176, v172, v148
	ds_bpermute_b32 v179, v172, v175
	ds_bpermute_b32 v178, v172, v174
	v_cmp_lt_i32_e32 vcc, v173, v191
	v_add_u32_e32 v182, v152, v150
	s_waitcnt lgkmcnt(2)
	v_pk_add_f32 v[176:177], v[148:149], v[176:177]
	v_cndmask_b32_e32 v173, v171, v173, vcc
	v_lshlrev_b32_e32 v173, 2, v173
	s_waitcnt lgkmcnt(0)
	v_pk_add_f32 v[174:175], v[174:175], v[178:179]
	ds_bpermute_b32 v179, v173, v177
	ds_bpermute_b32 v178, v173, v176
	ds_bpermute_b32 v181, v173, v175
	ds_bpermute_b32 v180, v173, v174
	v_mov_b64_e32 v[148:149], s[22:23]
	v_ashrrev_i32_e32 v183, 31, v182
	s_waitcnt lgkmcnt(2)
	v_pk_add_f32 v[176:177], v[176:177], v[178:179]
	s_waitcnt lgkmcnt(0)
	v_pk_add_f32 v[174:175], v[174:175], v[180:181]
	v_pk_fma_f32 v[176:177], v[176:177], s[20:21], v[148:149] op_sel_hi:[1,0,0]
	v_pk_fma_f32 v[174:175], v[174:175], s[20:21], v[148:149] op_sel_hi:[1,0,0]
	v_mul_f32_e32 v150, 0x4b800000, v177
	v_cmp_gt_f32_e32 vcc, s68, v177
	v_mul_f32_e32 v152, 0x4b800000, v176
	v_mul_f32_e32 v178, 0x4b800000, v175
	v_cndmask_b32_e32 v150, v177, v150, vcc
	v_mul_f32_e32 v179, 0x4b800000, v174
	v_cmp_gt_f32_e64 s[8:9], s68, v176
	v_cmp_gt_f32_e64 s[10:11], s68, v175
	v_cmp_gt_f32_e64 s[12:13], s68, v174
	v_rsq_f32_e32 v150, v150
	v_cndmask_b32_e64 v152, v176, v152, s[8:9]
	v_cndmask_b32_e64 v175, v175, v178, s[10:11]
	v_cndmask_b32_e64 v174, v174, v179, s[12:13]
	v_rsq_f32_e32 v152, v152
	v_rsq_f32_e32 v175, v175
	v_rsq_f32_e32 v177, v174
	v_mul_f32_e32 v174, 0x45800000, v150
	v_cndmask_b32_e32 v174, v150, v174, vcc
	v_mul_f32_e32 v176, 0x45800000, v152
	v_mul_f32_e32 v178, 0x45800000, v175
	v_mul_f32_e32 v179, 0x45800000, v177
	v_pk_mul_f32 v[124:125], v[124:125], v[174:175] op_sel_hi:[1,0]
	v_pk_mul_f32 v[126:127], v[126:127], v[174:175] op_sel_hi:[1,0]
	v_cndmask_b32_e64 v176, v152, v176, s[8:9]
	v_cndmask_b32_e64 v152, v175, v178, s[10:11]
	v_cndmask_b32_e64 v150, v177, v179, s[12:13]
	v_pk_mul_f32 v[120:121], v[120:121], v[174:175] op_sel_hi:[1,0]
	v_pk_mul_f32 v[122:123], v[122:123], v[174:175] op_sel_hi:[1,0]
	v_pk_mul_f32 v[116:117], v[116:117], v[174:175] op_sel_hi:[1,0]
	v_mul_f32_e32 v175, 0xbfb8aa3b, v124
	v_mul_f32_e32 v178, 0xbfb8aa3b, v126
	v_mul_f32_e32 v179, 0xbfb8aa3b, v127
	v_exp_f32_e32 v175, v175
	v_exp_f32_e32 v178, v178
	v_exp_f32_e32 v179, v179
	v_mul_f32_e32 v177, 0xbfb8aa3b, v125
	v_mul_f32_e32 v184, 0xbfb8aa3b, v116
	v_exp_f32_e32 v177, v177
	v_add_f32_e32 v175, 1.0, v175
	v_add_f32_e32 v180, 1.0, v178
	v_add_f32_e32 v181, 1.0, v179
	v_rcp_f32_e32 v178, v175
	v_rcp_f32_e32 v180, v180
	v_rcp_f32_e32 v181, v181
	v_exp_f32_e32 v175, v184
	v_add_f32_e32 v177, 1.0, v177
	v_mul_f32_e32 v185, 0xbfb8aa3b, v117
	v_rcp_f32_e32 v179, v177
	v_pk_mul_f32 v[126:127], v[126:127], v[180:181]
	v_pk_mul_f32 v[118:119], v[118:119], v[174:175] op_sel_hi:[1,0]
	v_exp_f32_e32 v177, v185
	v_pk_mul_f32 v[122:123], v[122:123], v[126:127]
	v_mul_f32_e32 v126, 0xbfb8aa3b, v118
	v_mul_f32_e32 v127, 0xbfb8aa3b, v119
	v_exp_f32_e32 v126, v126
	v_exp_f32_e32 v127, v127
	v_pk_mul_f32 v[124:125], v[124:125], v[178:179]
	v_pk_mul_f32 v[112:113], v[112:113], v[174:175] op_sel_hi:[1,0]
	v_pk_mul_f32 v[120:121], v[120:121], v[124:125]
	v_add_f32_e32 v124, 1.0, v175
; __device__ __forceinline__ unsigned pk2(float lo, float hi) { f32x2_t v = {lo, hi}; bf16x2_t b = __builtin_convertvector(v, bf16x2_t); return __builtin_bit_cast(unsigned, b); }
; __device__ __forceinline__ float sigm(float x) { return frcp(1.f + fexp2(-LOG2E * x)); }
;   __device__ __forceinline__ void operator()(const pg8::f32x4 (&acc)[2][2][4][2], const pg8::Unit& u, int wr, int wc, int fr, int fq) const {
;     ...
;       for (int m = 0; m < 4; ++m) {
;         const float r = rs[m]; float v[8];
; #pragma unroll
;         for (int n = 0; n < 2; ++n)
; #pragma unroll
;           for (int c = 0; c < 4; ++c) { const float g = acc[ai][0][m][n][c] * r, uu = acc[ai][1][m][n][c] * r; v[4 * n + c] = g * sigm(g) * uu; }
;         u32x4 w; w.x = pk2(v[0], v[1]); w.y = pk2(v[2], v[3]); w.z = pk2(v[4], v[5]); w.w = pk2(v[6], v[7]);
;         *(u32x4*)(hbuf + (unsigned)(row0 + ai * 128 + m * 16) * DFF + col0) = w;
;       }
	v_add_f32_e32 v125, 1.0, v177
	v_rcp_f32_e32 v124, v124
	v_rcp_f32_e32 v125, v125
	v_add_f32_e32 v126, 1.0, v126
	v_add_f32_e32 v127, 1.0, v127
	v_rcp_f32_e32 v126, v126
	v_rcp_f32_e32 v127, v127
	v_pk_mul_f32 v[116:117], v[116:117], v[124:125]
	v_pk_mul_f32 v[114:115], v[114:115], v[174:175] op_sel_hi:[1,0]
	v_pk_mul_f32 v[112:113], v[112:113], v[116:117]
	v_pk_mul_f32 v[116:117], v[118:119], v[126:127]
	v_cvt_pk_bf16_f32 v118, v112, v113
	v_pk_mul_f32 v[114:115], v[114:115], v[116:117]
	v_cvt_pk_bf16_f32 v116, v120, v121
	v_cvt_pk_bf16_f32 v119, v114, v115
	v_mul_lo_u32 v114, v190, s69
	v_mov_b32_e32 v115, v137
	v_lshl_add_u64 v[120:121], v[114:115], 1, s[38:39]
	v_lshlrev_b64 v[112:113], 1, v[182:183]
	v_pk_mul_f32 v[108:109], v[108:109], v[176:177] op_sel_hi:[1,0]
	v_cvt_pk_bf16_f32 v117, v122, v123
	v_lshl_add_u64 v[120:121], v[120:121], 0, v[112:113]
	v_mul_f32_e32 v115, 0xbfb8aa3b, v108
	v_exp_f32_e32 v115, v115
	global_store_dwordx4 v[120:121], v[116:119], off
	v_pk_mul_f32 v[110:111], v[110:111], v[176:177] op_sel_hi:[1,0]
	v_pk_mul_f32 v[100:101], v[100:101], v[176:177] op_sel_hi:[1,0]
	v_mul_f32_e32 v116, 0xbfb8aa3b, v109
	v_exp_f32_e32 v117, v116
	v_add_f32_e32 v115, 1.0, v115
	v_rcp_f32_e32 v116, v115
	v_pk_mul_f32 v[104:105], v[104:105], v[176:177] op_sel_hi:[1,0]
	v_add_f32_e32 v115, 1.0, v117
	v_mul_f32_e32 v117, 0xbfb8aa3b, v110
	v_exp_f32_e32 v118, v117
	v_mul_f32_e32 v117, 0xbfb8aa3b, v111
	v_exp_f32_e32 v119, v117
	v_rcp_f32_e32 v117, v115
	v_add_f32_e32 v115, 1.0, v118
	v_rcp_f32_e32 v118, v115
	v_add_f32_e32 v115, 1.0, v119
	v_rcp_f32_e32 v119, v115
	v_pk_mul_f32 v[108:109], v[108:109], v[116:117]
	v_pk_mul_f32 v[102:103], v[102:103], v[176:177] op_sel_hi:[1,0]
	v_pk_mul_f32 v[100:101], v[100:101], v[108:109]
	v_pk_mul_f32 v[108:109], v[110:111], v[118:119]
	v_mul_f32_e32 v110, 0xbfb8aa3b, v104
	v_exp_f32_e32 v110, v110
	v_pk_mul_f32 v[102:103], v[102:103], v[108:109]
	v_mul_f32_e32 v108, 0xbfb8aa3b, v105
	v_pk_mul_f32 v[106:107], v[106:107], v[176:177] op_sel_hi:[1,0]
	v_exp_f32_e32 v109, v108
	v_add_f32_e32 v108, 1.0, v110
	v_mul_f32_e32 v110, 0xbfb8aa3b, v106
	v_mul_f32_e32 v111, 0xbfb8aa3b, v107
	v_exp_f32_e32 v110, v110
	v_exp_f32_e32 v111, v111
	v_add_f32_e32 v109, 1.0, v109
	v_rcp_f32_e32 v108, v108
	v_rcp_f32_e32 v109, v109
	v_add_f32_e32 v110, 1.0, v110
	v_add_f32_e32 v111, 1.0, v111
	v_rcp_f32_e32 v110, v110
	v_rcp_f32_e32 v111, v111
	v_pk_mul_f32 v[96:97], v[96:97], v[176:177] op_sel_hi:[1,0]
	v_pk_mul_f32 v[104:105], v[104:105], v[108:109]
	v_pk_mul_f32 v[92:93], v[92:93], v[152:153] op_sel_hi:[1,0]
	v_pk_mul_f32 v[104:105], v[96:97], v[104:105]
	v_pk_mul_f32 v[96:97], v[98:99], v[176:177] op_sel_hi:[1,0]
	v_pk_mul_f32 v[98:99], v[106:107], v[110:111]
	v_pk_mul_f32 v[94:95], v[94:95], v[152:153] op_sel_hi:[1,0]
	v_pk_mul_f32 v[106:107], v[96:97], v[98:99]
	v_cvt_pk_bf16_f32 v96, v100, v101
	v_add_u32_e32 v100, 0xb000, v114
	v_mov_b32_e32 v101, v137
	v_lshl_add_u64 v[100:101], v[100:101], 1, s[38:39]
	v_cvt_pk_bf16_f32 v97, v102, v103
	v_cvt_pk_bf16_f32 v98, v104, v105
	v_cvt_pk_bf16_f32 v99, v106, v107
	v_lshl_add_u64 v[100:101], v[100:101], 0, v[112:113]
	v_mul_f32_e32 v102, 0xbfb8aa3b, v92
	global_store_dwordx4 v[100:101], v[96:99], off
	v_exp_f32_e32 v102, v102
	v_pk_mul_f32 v[84:85], v[84:85], v[152:153] op_sel_hi:[1,0]
	v_mul_f32_e32 v96, 0xbfb8aa3b, v93
	v_exp_f32_e32 v97, v96
	v_mul_f32_e32 v98, 0xbfb8aa3b, v94
	v_mul_f32_e32 v99, 0xbfb8aa3b, v95
	v_exp_f32_e32 v98, v98
	v_exp_f32_e32 v99, v99
	v_add_f32_e32 v96, 1.0, v102
	v_add_f32_e32 v97, 1.0, v97
	v_rcp_f32_e32 v96, v96
	v_rcp_f32_e32 v97, v97
	v_add_f32_e32 v98, 1.0, v98
	v_add_f32_e32 v99, 1.0, v99
	v_rcp_f32_e32 v98, v98
	v_rcp_f32_e32 v99, v99
	v_pk_mul_f32 v[92:93], v[92:93], v[96:97]
	v_pk_mul_f32 v[88:89], v[88:89], v[152:153] op_sel_hi:[1,0]
	v_pk_mul_f32 v[84:85], v[84:85], v[92:93]
	v_pk_mul_f32 v[92:93], v[94:95], v[98:99]
	v_mul_f32_e32 v94, 0xbfb8aa3b, v88
	v_exp_f32_e32 v94, v94
	v_pk_mul_f32 v[86:87], v[86:87], v[152:153] op_sel_hi:[1,0]
	v_pk_mul_f32 v[90:91], v[90:91], v[152:153] op_sel_hi:[1,0]
	v_pk_mul_f32 v[86:87], v[86:87], v[92:93]
	v_mul_f32_e32 v92, 0xbfb8aa3b, v89
	v_exp_f32_e32 v93, v92
	v_add_f32_e32 v92, 1.0, v94
	v_mul_f32_e32 v94, 0xbfb8aa3b, v90
	v_mul_f32_e32 v95, 0xbfb8aa3b, v91
	v_exp_f32_e32 v94, v94
	v_exp_f32_e32 v95, v95
	v_add_f32_e32 v93, 1.0, v93
	v_rcp_f32_e32 v92, v92
	v_rcp_f32_e32 v93, v93
	v_add_f32_e32 v94, 1.0, v94
	v_add_f32_e32 v95, 1.0, v95
	v_rcp_f32_e32 v94, v94
	v_rcp_f32_e32 v95, v95
	v_pk_mul_f32 v[80:81], v[80:81], v[152:153] op_sel_hi:[1,0]
	v_pk_mul_f32 v[88:89], v[88:89], v[92:93]
	v_pk_mul_f32 v[76:77], v[76:77], v[150:151] op_sel_hi:[1,0]
	v_pk_mul_f32 v[88:89], v[80:81], v[88:89]
	v_pk_mul_f32 v[80:81], v[82:83], v[152:153] op_sel_hi:[1,0]
	v_pk_mul_f32 v[82:83], v[90:91], v[94:95]
	v_pk_mul_f32 v[78:79], v[78:79], v[150:151] op_sel_hi:[1,0]
	v_pk_mul_f32 v[90:91], v[80:81], v[82:83]
	v_cvt_pk_bf16_f32 v80, v84, v85
	v_add_u32_e32 v84, 0x16000, v114
	v_mov_b32_e32 v85, v137
	v_lshl_add_u64 v[84:85], v[84:85], 1, s[38:39]
	v_cvt_pk_bf16_f32 v81, v86, v87
	v_cvt_pk_bf16_f32 v82, v88, v89
	v_cvt_pk_bf16_f32 v83, v90, v91
	v_lshl_add_u64 v[84:85], v[84:85], 0, v[112:113]
	v_mul_f32_e32 v86, 0xbfb8aa3b, v76
	global_store_dwordx4 v[84:85], v[80:83], off
	v_exp_f32_e32 v86, v86
	v_pk_mul_f32 v[68:69], v[68:69], v[150:151] op_sel_hi:[1,0]
	v_mul_f32_e32 v80, 0xbfb8aa3b, v77
	v_exp_f32_e32 v81, v80
	v_mul_f32_e32 v82, 0xbfb8aa3b, v78
	v_mul_f32_e32 v83, 0xbfb8aa3b, v79
	v_exp_f32_e32 v82, v82
	v_exp_f32_e32 v83, v83
	v_add_f32_e32 v80, 1.0, v86
	v_add_f32_e32 v81, 1.0, v81
; __device__ __forceinline__ unsigned pk2(float lo, float hi) { f32x2_t v = {lo, hi}; bf16x2_t b = __builtin_convertvector(v, bf16x2_t); return __builtin_bit_cast(unsigned, b); }
; __device__ __forceinline__ float sigm(float x) { return frcp(1.f + fexp2(-LOG2E * x)); }
;   __device__ __forceinline__ void operator()(const pg8::f32x4 (&acc)[2][2][4][2], const pg8::Unit& u, int wr, int wc, int fr, int fq) const {
;     ...
;       for (int m = 0; m < 4; ++m) { const f32x4 a = *(const f32x4*)(ssq + (unsigned)(row0 + ai * 128 + m * 16) * 16 + 4 * fq); rs[m] = (a[0] + a[1]) + (a[2] + a[3]); }
; #pragma unroll
;       for (int m = 0; m < 4; ++m) { float v = rs[m]; v += __shfl_xor(v, 16); v += __shfl_xor(v, 32); rs[m] = rsqrtf(v * (1.f / 1024.f) + EPS); }
; #pragma unroll
;       for (int m = 0; m < 4; ++m) {
;         const float r = rs[m]; float v[8];
; #pragma unroll
;         for (int n = 0; n < 2; ++n)
; #pragma unroll
;           for (int c = 0; c < 4; ++c) { const float g = acc[ai][0][m][n][c] * r, uu = acc[ai][1][m][n][c] * r; v[4 * n + c] = g * sigm(g) * uu; }
;         u32x4 w; w.x = pk2(v[0], v[1]); w.y = pk2(v[2], v[3]); w.z = pk2(v[4], v[5]); w.w = pk2(v[6], v[7]);
;         *(u32x4*)(hbuf + (unsigned)(row0 + ai * 128 + m * 16) * DFF + col0) = w;
;       }
	v_rcp_f32_e32 v80, v80
	v_rcp_f32_e32 v81, v81
	v_add_f32_e32 v82, 1.0, v82
	v_add_f32_e32 v83, 1.0, v83
	v_rcp_f32_e32 v82, v82
	v_rcp_f32_e32 v83, v83
	v_pk_mul_f32 v[76:77], v[76:77], v[80:81]
	v_pk_mul_f32 v[72:73], v[72:73], v[150:151] op_sel_hi:[1,0]
	v_pk_mul_f32 v[68:69], v[68:69], v[76:77]
	v_pk_mul_f32 v[76:77], v[78:79], v[82:83]
	v_mul_f32_e32 v78, 0xbfb8aa3b, v72
	v_exp_f32_e32 v78, v78
	v_pk_mul_f32 v[70:71], v[70:71], v[150:151] op_sel_hi:[1,0]
	v_pk_mul_f32 v[74:75], v[74:75], v[150:151] op_sel_hi:[1,0]
	v_pk_mul_f32 v[70:71], v[70:71], v[76:77]
	v_mul_f32_e32 v76, 0xbfb8aa3b, v73
	v_exp_f32_e32 v77, v76
	v_add_f32_e32 v76, 1.0, v78
	v_mul_f32_e32 v78, 0xbfb8aa3b, v74
	v_mul_f32_e32 v79, 0xbfb8aa3b, v75
	v_exp_f32_e32 v78, v78
	v_exp_f32_e32 v79, v79
	v_add_f32_e32 v77, 1.0, v77
	v_rcp_f32_e32 v76, v76
	v_rcp_f32_e32 v77, v77
	v_add_f32_e32 v78, 1.0, v78
	v_add_f32_e32 v79, 1.0, v79
	v_rcp_f32_e32 v78, v78
	v_rcp_f32_e32 v79, v79
	v_pk_mul_f32 v[64:65], v[64:65], v[150:151] op_sel_hi:[1,0]
	v_pk_mul_f32 v[72:73], v[72:73], v[76:77]
	s_nop 0
	v_pk_mul_f32 v[72:73], v[64:65], v[72:73]
	v_pk_mul_f32 v[64:65], v[66:67], v[150:151] op_sel_hi:[1,0]
	v_pk_mul_f32 v[66:67], v[74:75], v[78:79]
	s_nop 0
	v_pk_mul_f32 v[74:75], v[64:65], v[66:67]
	v_cvt_pk_bf16_f32 v64, v68, v69
	v_add_u32_e32 v68, 0x21000, v114
	v_mov_b32_e32 v69, v137
	v_lshl_add_u64 v[68:69], v[68:69], 1, s[38:39]
	v_cvt_pk_bf16_f32 v65, v70, v71
	v_cvt_pk_bf16_f32 v66, v72, v73
	v_cvt_pk_bf16_f32 v67, v74, v75
	v_lshl_add_u64 v[68:69], v[68:69], 0, v[112:113]
	global_store_dwordx4 v[68:69], v[64:67], off
	v_add_u32_e32 v136, 0x58000, v114
	v_mov_b64_e32 v[72:73], v[208:209]
	v_mov_b64_e32 v[74:75], v[210:211]
	v_mov_b64_e32 v[76:77], v[212:213]
	v_mov_b64_e32 v[78:79], v[214:215]
	v_mov_b64_e32 v[64:65], v[200:201]
	v_mov_b64_e32 v[66:67], v[202:203]
	v_mov_b64_e32 v[68:69], v[204:205]
	v_mov_b64_e32 v[70:71], v[206:207]
	v_mov_b32_e32 v80, v65
	v_mov_b32_e32 v81, v66
	v_mov_b32_e32 v65, v67
	v_mov_b32_e32 v66, v69
	v_mov_b32_e32 v67, v70
	v_mov_b32_e32 v69, v71
	v_pk_add_f32 v[64:65], v[80:81], v[64:65]
	v_pk_add_f32 v[66:67], v[66:67], v[68:69]
	v_mov_b32_e32 v69, v64
	v_mov_b32_e32 v68, v66
	v_mov_b32_e32 v64, v67
	v_pk_add_f32 v[64:65], v[68:69], v[64:65]
	ds_bpermute_b32 v67, v172, v65
	ds_bpermute_b32 v66, v172, v64
	v_mov_b32_e32 v68, v73
	v_mov_b32_e32 v69, v74
	v_mov_b32_e32 v73, v75
	v_mov_b32_e32 v70, v77
	s_waitcnt lgkmcnt(0)
	v_pk_add_f32 v[64:65], v[64:65], v[66:67]
	ds_bpermute_b32 v67, v173, v65
	ds_bpermute_b32 v66, v173, v64
	v_mov_b32_e32 v71, v78
	v_mov_b32_e32 v77, v79
	v_pk_add_f32 v[68:69], v[68:69], v[72:73]
	v_pk_add_f32 v[70:71], v[70:71], v[76:77]
	s_waitcnt lgkmcnt(0)
	v_pk_add_f32 v[64:65], v[64:65], v[66:67]
	v_mov_b32_e32 v67, v68
	v_pk_fma_f32 v[64:65], v[64:65], s[20:21], v[148:149] op_sel_hi:[1,0,0]
	v_mov_b32_e32 v68, v71
	v_mul_f32_e32 v66, 0x4b800000, v65
	v_cmp_gt_f32_e32 vcc, s68, v65
	v_cmp_gt_f32_e64 s[8:9], s68, v64
	s_nop 0
	v_cndmask_b32_e32 v65, v65, v66, vcc
	v_mov_b32_e32 v66, v70
	v_pk_add_f32 v[66:67], v[66:67], v[68:69]
	ds_bpermute_b32 v69, v172, v67
	ds_bpermute_b32 v68, v172, v66
	v_rsq_f32_e32 v72, v65
	v_mul_f32_e32 v65, 0x4b800000, v64
	v_cndmask_b32_e64 v64, v64, v65, s[8:9]
	v_rsq_f32_e32 v70, v64
	s_waitcnt lgkmcnt(0)
	v_pk_add_f32 v[64:65], v[66:67], v[68:69]
	ds_bpermute_b32 v67, v173, v65
	ds_bpermute_b32 v66, v173, v64
	v_mul_f32_e32 v68, 0x45800000, v72
	v_cndmask_b32_e32 v68, v72, v68, vcc
	v_mul_f32_e32 v69, 0x45800000, v70
	v_pk_mul_f32 v[62:63], v[62:63], v[68:69] op_sel_hi:[1,0]
	s_waitcnt lgkmcnt(0)
	v_pk_add_f32 v[64:65], v[64:65], v[66:67]
	v_pk_mul_f32 v[56:57], v[56:57], v[68:69] op_sel_hi:[1,0]
	v_pk_fma_f32 v[64:65], v[64:65], s[20:21], v[148:149] op_sel_hi:[1,0,0]
	v_pk_mul_f32 v[54:55], v[54:55], v[68:69] op_sel_hi:[1,0]
	v_mul_f32_e32 v66, 0x4b800000, v65
	v_cmp_gt_f32_e32 vcc, s68, v65
	v_cmp_gt_f32_e64 s[10:11], s68, v64
	v_pk_mul_f32 v[58:59], v[58:59], v[68:69] op_sel_hi:[1,0]
	v_cndmask_b32_e32 v65, v65, v66, vcc
	v_mul_f32_e32 v66, 0x4b800000, v64
	v_rsq_f32_e32 v65, v65
	v_cndmask_b32_e64 v64, v64, v66, s[10:11]
	v_rsq_f32_e32 v67, v64
	v_cndmask_b32_e64 v66, v70, v69, s[8:9]
	v_mul_f32_e32 v64, 0x45800000, v65
	v_pk_mul_f32 v[70:71], v[60:61], v[68:69] op_sel_hi:[1,0]
	v_cndmask_b32_e32 v64, v65, v64, vcc
	v_mul_f32_e32 v65, 0x45800000, v67
	v_mul_f32_e32 v60, 0xbfb8aa3b, v70
	v_exp_f32_e32 v61, v60
	v_cndmask_b32_e64 v60, v67, v65, s[10:11]
	v_mul_f32_e32 v65, 0xbfb8aa3b, v71
	v_exp_f32_e32 v65, v65
	v_add_f32_e32 v61, 1.0, v61
	v_rcp_f32_e32 v72, v61
	v_mul_f32_e32 v67, 0xbfb8aa3b, v63
	v_add_f32_e32 v61, 1.0, v65
	v_mul_f32_e32 v65, 0xbfb8aa3b, v62
	v_exp_f32_e32 v65, v65
	v_exp_f32_e32 v67, v67
	v_rcp_f32_e32 v73, v61
	v_pk_mul_f32 v[52:53], v[52:53], v[68:69] op_sel_hi:[1,0]
	v_add_f32_e32 v61, 1.0, v65
	v_rcp_f32_e32 v74, v61
	v_add_f32_e32 v61, 1.0, v67
	v_rcp_f32_e32 v75, v61
	v_mul_f32_e32 v61, 0xbfb8aa3b, v56
	v_exp_f32_e32 v61, v61
	v_pk_mul_f32 v[70:71], v[70:71], v[72:73]
	v_pk_mul_f32 v[62:63], v[62:63], v[74:75]
	v_pk_mul_f32 v[52:53], v[52:53], v[70:71]
	v_pk_mul_f32 v[54:55], v[54:55], v[62:63]
	v_mul_f32_e32 v62, 0xbfb8aa3b, v57
	v_exp_f32_e32 v63, v62
	v_add_f32_e32 v61, 1.0, v61
	v_rcp_f32_e32 v62, v61
	v_pk_mul_f32 v[48:49], v[48:49], v[68:69] op_sel_hi:[1,0]
	v_add_f32_e32 v61, 1.0, v63
	v_mul_f32_e32 v63, 0xbfb8aa3b, v58
	v_exp_f32_e32 v65, v63
	v_mul_f32_e32 v63, 0xbfb8aa3b, v59
	v_exp_f32_e32 v67, v63
	v_rcp_f32_e32 v63, v61
	v_add_f32_e32 v61, 1.0, v65
	v_rcp_f32_e32 v70, v61
	v_add_f32_e32 v61, 1.0, v67
	v_rcp_f32_e32 v71, v61
; __device__ __forceinline__ unsigned pk2(float lo, float hi) { f32x2_t v = {lo, hi}; bf16x2_t b = __builtin_convertvector(v, bf16x2_t); return __builtin_bit_cast(unsigned, b); }
; __device__ __forceinline__ float sigm(float x) { return frcp(1.f + fexp2(-LOG2E * x)); }
; #define PG8_BAR __builtin_amdgcn_s_barrier()
; template <class Epi, class Sched, bool ALIGN_EPI = false, bool SP2 = false, bool F16 = false, bool TOKPERM = false>
; __device__ __forceinline__ void gemm_phase(PG8_LAS unsigned char* lds, const Gemm g, const Sched& S, const Epi& E, int wv) {
;     ...
;         if constexpr (ALIGN_EPI) { if (wr == 0) PG8_BAR; }
;         if constexpr (!Epi::AFTER_DRAIN) { E(acc, cur, wr, wc, fr, fq); S.done(cur); }
;         if (!has_next) break;
; #pragma unroll
;         for (int a = 0; a < 2; ++a)
; #pragma unroll
;             for (int b = 0; b < 2; ++b)
; #pragma unroll
;                 for (int m = 0; m < 4; ++m)
; #pragma unroll
;                     for (int n = 0; n < 2; ++n) acc[a][b][m][n] = (f32x4){0.f, 0.f, 0.f, 0.f};
;         cur = nxt; cA = nA; cB = nB; ++ui;
;         if constexpr (ALIGN_EPI) { if (wr == 1) PG8_BAR; }
;   __device__ __forceinline__ void operator()(const pg8::f32x4 (&acc)[2][2][4][2], const pg8::Unit& u, int wr, int wc, int fr, int fq) const {
;     ...
;       for (int m = 0; m < 4; ++m) {
;         const float r = rs[m]; float v[8];
; #pragma unroll
;         for (int n = 0; n < 2; ++n)
; #pragma unroll
;           for (int c = 0; c < 4; ++c) { const float g = acc[ai][0][m][n][c] * r, uu = acc[ai][1][m][n][c] * r; v[4 * n + c] = g * sigm(g) * uu; }
;         u32x4 w; w.x = pk2(v[0], v[1]); w.y = pk2(v[2], v[3]); w.z = pk2(v[4], v[5]); w.w = pk2(v[6], v[7]);
;         *(u32x4*)(hbuf + (unsigned)(row0 + ai * 128 + m * 16) * DFF + col0) = w;
;       }
	v_pk_mul_f32 v[56:57], v[56:57], v[62:63]
	v_pk_mul_f32 v[44:45], v[44:45], v[66:67] op_sel_hi:[1,0]
	v_pk_mul_f32 v[56:57], v[48:49], v[56:57]
	v_pk_mul_f32 v[48:49], v[50:51], v[68:69] op_sel_hi:[1,0]
	v_pk_mul_f32 v[50:51], v[58:59], v[70:71]
	v_pk_mul_f32 v[46:47], v[46:47], v[66:67] op_sel_hi:[1,0]
	v_pk_mul_f32 v[58:59], v[48:49], v[50:51]
	v_cvt_pk_bf16_f32 v48, v52, v53
	v_lshl_add_u64 v[52:53], v[136:137], 1, s[38:39]
	v_cvt_pk_bf16_f32 v49, v54, v55
	v_cvt_pk_bf16_f32 v50, v56, v57
	v_cvt_pk_bf16_f32 v51, v58, v59
	v_lshl_add_u64 v[52:53], v[52:53], 0, v[112:113]
	v_mul_f32_e32 v54, 0xbfb8aa3b, v44
	global_store_dwordx4 v[52:53], v[48:51], off
	v_exp_f32_e32 v54, v54
	v_pk_mul_f32 v[36:37], v[36:37], v[66:67] op_sel_hi:[1,0]
	v_mul_f32_e32 v48, 0xbfb8aa3b, v45
	v_exp_f32_e32 v49, v48
	v_mul_f32_e32 v50, 0xbfb8aa3b, v46
	v_mul_f32_e32 v51, 0xbfb8aa3b, v47
	v_exp_f32_e32 v50, v50
	v_exp_f32_e32 v51, v51
	v_add_f32_e32 v48, 1.0, v54
	v_add_f32_e32 v49, 1.0, v49
	v_rcp_f32_e32 v48, v48
	v_rcp_f32_e32 v49, v49
	v_add_f32_e32 v50, 1.0, v50
	v_add_f32_e32 v51, 1.0, v51
	v_rcp_f32_e32 v50, v50
	v_rcp_f32_e32 v51, v51
	v_pk_mul_f32 v[44:45], v[44:45], v[48:49]
	v_pk_mul_f32 v[40:41], v[40:41], v[66:67] op_sel_hi:[1,0]
	v_pk_mul_f32 v[36:37], v[36:37], v[44:45]
	v_pk_mul_f32 v[44:45], v[46:47], v[50:51]
	v_mul_f32_e32 v46, 0xbfb8aa3b, v40
	v_exp_f32_e32 v46, v46
	v_pk_mul_f32 v[38:39], v[38:39], v[66:67] op_sel_hi:[1,0]
	v_pk_mul_f32 v[42:43], v[42:43], v[66:67] op_sel_hi:[1,0]
	v_pk_mul_f32 v[38:39], v[38:39], v[44:45]
	v_mul_f32_e32 v44, 0xbfb8aa3b, v41
	v_exp_f32_e32 v45, v44
	v_add_f32_e32 v44, 1.0, v46
	v_mul_f32_e32 v46, 0xbfb8aa3b, v42
	v_mul_f32_e32 v47, 0xbfb8aa3b, v43
	v_exp_f32_e32 v46, v46
	v_exp_f32_e32 v47, v47
	v_add_f32_e32 v45, 1.0, v45
	v_rcp_f32_e32 v44, v44
	v_rcp_f32_e32 v45, v45
	v_add_f32_e32 v46, 1.0, v46
	v_add_f32_e32 v47, 1.0, v47
	v_rcp_f32_e32 v46, v46
	v_rcp_f32_e32 v47, v47
	v_pk_mul_f32 v[32:33], v[32:33], v[66:67] op_sel_hi:[1,0]
	v_pk_mul_f32 v[40:41], v[40:41], v[44:45]
	v_add_u32_e32 v136, 0x63000, v114
	v_pk_mul_f32 v[40:41], v[32:33], v[40:41]
	v_pk_mul_f32 v[32:33], v[34:35], v[66:67] op_sel_hi:[1,0]
	v_pk_mul_f32 v[34:35], v[42:43], v[46:47]
	v_pk_mul_f32 v[28:29], v[28:29], v[64:65] op_sel_hi:[1,0]
	v_pk_mul_f32 v[42:43], v[32:33], v[34:35]
	v_cvt_pk_bf16_f32 v32, v36, v37
	v_lshl_add_u64 v[36:37], v[136:137], 1, s[38:39]
	v_cvt_pk_bf16_f32 v33, v38, v39
	v_cvt_pk_bf16_f32 v34, v40, v41
	v_cvt_pk_bf16_f32 v35, v42, v43
	v_lshl_add_u64 v[36:37], v[36:37], 0, v[112:113]
	v_mul_f32_e32 v38, 0xbfb8aa3b, v28
	global_store_dwordx4 v[36:37], v[32:35], off
	v_pk_mul_f32 v[30:31], v[30:31], v[64:65] op_sel_hi:[1,0]
	v_exp_f32_e32 v38, v38
	v_mul_f32_e32 v32, 0xbfb8aa3b, v29
	v_exp_f32_e32 v33, v32
	v_mul_f32_e32 v34, 0xbfb8aa3b, v30
	v_mul_f32_e32 v35, 0xbfb8aa3b, v31
	v_exp_f32_e32 v34, v34
	v_exp_f32_e32 v35, v35
	v_add_f32_e32 v32, 1.0, v38
	v_add_f32_e32 v33, 1.0, v33
	v_rcp_f32_e32 v32, v32
	v_rcp_f32_e32 v33, v33
	v_add_f32_e32 v34, 1.0, v34
	v_add_f32_e32 v35, 1.0, v35
	v_rcp_f32_e32 v34, v34
	v_rcp_f32_e32 v35, v35
	v_pk_mul_f32 v[20:21], v[20:21], v[64:65] op_sel_hi:[1,0]
	v_pk_mul_f32 v[28:29], v[28:29], v[32:33]
	v_pk_mul_f32 v[24:25], v[24:25], v[64:65] op_sel_hi:[1,0]
	v_pk_mul_f32 v[20:21], v[20:21], v[28:29]
	v_pk_mul_f32 v[28:29], v[30:31], v[34:35]
	v_mul_f32_e32 v30, 0xbfb8aa3b, v24
	v_exp_f32_e32 v30, v30
	v_pk_mul_f32 v[22:23], v[22:23], v[64:65] op_sel_hi:[1,0]
	v_pk_mul_f32 v[26:27], v[26:27], v[64:65] op_sel_hi:[1,0]
	v_pk_mul_f32 v[22:23], v[22:23], v[28:29]
	v_mul_f32_e32 v28, 0xbfb8aa3b, v25
	v_exp_f32_e32 v29, v28
	v_add_f32_e32 v28, 1.0, v30
	v_mul_f32_e32 v30, 0xbfb8aa3b, v26
	v_mul_f32_e32 v31, 0xbfb8aa3b, v27
	v_exp_f32_e32 v30, v30
	v_exp_f32_e32 v31, v31
	v_add_f32_e32 v29, 1.0, v29
	v_rcp_f32_e32 v28, v28
	v_rcp_f32_e32 v29, v29
	v_add_f32_e32 v30, 1.0, v30
	v_add_f32_e32 v31, 1.0, v31
	v_rcp_f32_e32 v30, v30
	v_rcp_f32_e32 v31, v31
	v_pk_mul_f32 v[16:17], v[16:17], v[64:65] op_sel_hi:[1,0]
	v_pk_mul_f32 v[24:25], v[24:25], v[28:29]
	v_add_u32_e32 v136, 0x6e000, v114
	v_pk_mul_f32 v[24:25], v[16:17], v[24:25]
	v_pk_mul_f32 v[16:17], v[18:19], v[64:65] op_sel_hi:[1,0]
	v_pk_mul_f32 v[18:19], v[26:27], v[30:31]
	v_pk_mul_f32 v[12:13], v[12:13], v[60:61] op_sel_hi:[1,0]
	v_pk_mul_f32 v[26:27], v[16:17], v[18:19]
	v_cvt_pk_bf16_f32 v16, v20, v21
	v_lshl_add_u64 v[20:21], v[136:137], 1, s[38:39]
	v_cvt_pk_bf16_f32 v17, v22, v23
	v_cvt_pk_bf16_f32 v18, v24, v25
	v_cvt_pk_bf16_f32 v19, v26, v27
	v_lshl_add_u64 v[20:21], v[20:21], 0, v[112:113]
	v_mul_f32_e32 v22, 0xbfb8aa3b, v12
	global_store_dwordx4 v[20:21], v[16:19], off
	v_pk_mul_f32 v[14:15], v[14:15], v[60:61] op_sel_hi:[1,0]
	v_exp_f32_e32 v22, v22
	v_mul_f32_e32 v16, 0xbfb8aa3b, v13
	v_exp_f32_e32 v17, v16
	v_mul_f32_e32 v18, 0xbfb8aa3b, v14
	v_mul_f32_e32 v19, 0xbfb8aa3b, v15
	v_exp_f32_e32 v18, v18
	v_exp_f32_e32 v19, v19
	v_add_f32_e32 v16, 1.0, v22
	v_add_f32_e32 v17, 1.0, v17
	v_rcp_f32_e32 v16, v16
	v_rcp_f32_e32 v17, v17
	v_add_f32_e32 v18, 1.0, v18
	v_add_f32_e32 v19, 1.0, v19
	v_rcp_f32_e32 v18, v18
	v_rcp_f32_e32 v19, v19
	v_pk_mul_f32 v[4:5], v[4:5], v[60:61] op_sel_hi:[1,0]
	v_pk_mul_f32 v[12:13], v[12:13], v[16:17]
	v_pk_mul_f32 v[8:9], v[8:9], v[60:61] op_sel_hi:[1,0]
	v_pk_mul_f32 v[4:5], v[4:5], v[12:13]
	v_pk_mul_f32 v[12:13], v[14:15], v[18:19]
	v_mul_f32_e32 v14, 0xbfb8aa3b, v8
	v_exp_f32_e32 v14, v14
	v_pk_mul_f32 v[6:7], v[6:7], v[60:61] op_sel_hi:[1,0]
	v_pk_mul_f32 v[10:11], v[10:11], v[60:61] op_sel_hi:[1,0]
	v_pk_mul_f32 v[6:7], v[6:7], v[12:13]
	v_mul_f32_e32 v12, 0xbfb8aa3b, v9
	v_exp_f32_e32 v13, v12
	v_add_f32_e32 v12, 1.0, v14
	v_mul_f32_e32 v14, 0xbfb8aa3b, v10
	v_mul_f32_e32 v15, 0xbfb8aa3b, v11
	v_exp_f32_e32 v14, v14
	v_exp_f32_e32 v15, v15
	v_add_f32_e32 v13, 1.0, v13
	v_rcp_f32_e32 v12, v12
	v_rcp_f32_e32 v13, v13
	v_add_f32_e32 v14, 1.0, v14
	v_add_f32_e32 v15, 1.0, v15
	v_rcp_f32_e32 v14, v14
	v_rcp_f32_e32 v15, v15
	v_pk_mul_f32 v[0:1], v[0:1], v[60:61] op_sel_hi:[1,0]
	v_pk_mul_f32 v[8:9], v[8:9], v[12:13]
	v_add_u32_e32 v136, 0x79000, v114
	v_pk_mul_f32 v[8:9], v[0:1], v[8:9]
	v_pk_mul_f32 v[0:1], v[2:3], v[60:61] op_sel_hi:[1,0]
	v_pk_mul_f32 v[2:3], v[10:11], v[14:15]
	s_andn2_b64 vcc, exec, s[6:7]
	v_pk_mul_f32 v[10:11], v[0:1], v[2:3]
	v_cvt_pk_bf16_f32 v0, v4, v5
	v_lshl_add_u64 v[4:5], v[136:137], 1, s[38:39]
	v_cvt_pk_bf16_f32 v1, v6, v7
	v_cvt_pk_bf16_f32 v2, v8, v9
	v_cvt_pk_bf16_f32 v3, v10, v11
	v_lshl_add_u64 v[4:5], v[4:5], 0, v[112:113]
	global_store_dwordx4 v[4:5], v[0:3], off
	s_mov_b64 s[6:7], -1
	s_cbranch_vccnz .LBB0_946
	s_andn2_b64 vcc, exec, s[14:15]
	s_cbranch_vccnz .LBB0_945
	s_barrier
	s_branch .LBB0_945

; __device__ __forceinline__ unsigned pk2(float lo, float hi) { f32x2_t v = {lo, hi}; bf16x2_t b = __builtin_convertvector(v, bf16x2_t); return __builtin_bit_cast(unsigned, b); }
; __device__ __forceinline__ float sigm(float x) { return frcp(1.f + fexp2(-LOG2E * x)); }
;   __device__ __forceinline__ void operator()(const pg8::f32x4 (&acc)[2][2][4][2], const pg8::Unit& u, int wr, int wc, int fr, int fq) const {
;     int z; asm volatile("v_mov_b32 %0, 0" : "=v"(z));
;     const int row0 = u.pm * 256 + wr * 64 + fr + z, col0 = u.pn * 128 + wc * 32 + 8 * fq + z;
; #pragma unroll
;     for (int ai = 0; ai < 2; ++ai) {
;       float rs[4];
; #pragma unroll
;       for (int m = 0; m < 4; ++m) { const f32x4 a = *(const f32x4*)(ssq + (unsigned)(row0 + ai * 128 + m * 16) * 16 + 4 * fq); rs[m] = (a[0] + a[1]) + (a[2] + a[3]); }
; #pragma unroll
;       for (int m = 0; m < 4; ++m) { float v = rs[m]; v += __shfl_xor(v, 16); v += __shfl_xor(v, 32); rs[m] = rsqrtf(v * (1.f / 1024.f) + EPS); }
; #pragma unroll
;       for (int m = 0; m < 4; ++m) {
;         const float r = rs[m]; float v[8];
; #pragma unroll
;         for (int n = 0; n < 2; ++n)
; #pragma unroll
;           for (int c = 0; c < 4; ++c) { const float g = acc[ai][0][m][n][c] * r, uu = acc[ai][1][m][n][c] * r; v[4 * n + c] = g * sigm(g) * uu; }
;         u32x4 w; w.x = pk2(v[0], v[1]); w.y = pk2(v[2], v[3]); w.z = pk2(v[4], v[5]); w.w = pk2(v[6], v[7]);
.LBB0_1610:
	s_lshl_b32 s6, s6, 8
	v_mov_b32 v150, 0
	v_xor_b32_e32 v173, 32, v171
	v_add3_u32 v190, s6, v151, v150
	v_lshlrev_b32_e32 v136, 4, v190
	v_lshl_add_u64 v[148:149], v[136:137], 2, v[138:139]
	global_load_dwordx4 v[174:177], v[148:149], off
	v_add_u32_e32 v148, 0x100, v136
	v_mov_b32_e32 v149, v137
	v_lshl_add_u64 v[148:149], v[148:149], 2, v[138:139]
	global_load_dwordx4 v[178:181], v[148:149], off
	v_add_u32_e32 v148, 0x200, v136
	v_mov_b32_e32 v149, v137
	v_lshl_add_u64 v[148:149], v[148:149], 2, v[138:139]
	global_load_dwordx4 v[182:185], v[148:149], off
	v_add_u32_e32 v148, 0x300, v136
	v_mov_b32_e32 v149, v137
	v_lshl_add_u64 v[148:149], v[148:149], 2, v[138:139]
	global_load_dwordx4 v[186:189], v[148:149], off
	v_add_u32_e32 v216, 0x800, v136
	v_mov_b32_e32 v217, v137
	v_lshl_add_u64 v[216:217], v[216:217], 2, v[138:139]
	global_load_dwordx4 v[200:203], v[216:217], off
	v_add_u32_e32 v216, 0x900, v136
	v_mov_b32_e32 v217, v137
	v_lshl_add_u64 v[216:217], v[216:217], 2, v[138:139]
	global_load_dwordx4 v[204:207], v[216:217], off
	v_add_u32_e32 v216, 0xa00, v136
	v_mov_b32_e32 v217, v137
	v_lshl_add_u64 v[216:217], v[216:217], 2, v[138:139]
	global_load_dwordx4 v[208:211], v[216:217], off
	v_add_u32_e32 v216, 0xb00, v136
	v_mov_b32_e32 v217, v137
	v_lshl_add_u64 v[216:217], v[216:217], 2, v[138:139]
	global_load_dwordx4 v[212:215], v[216:217], off
	v_and_b32_e32 v149, 64, v171
	v_xor_b32_e32 v148, 16, v171
	v_add_u32_e32 v191, 64, v149
	v_cmp_lt_i32_e32 vcc, v148, v191
	v_lshl_or_b32 v152, s7, 7, v154
	s_waitcnt vmcnt(0)
	v_mov_b32_e32 v149, v176
	v_cndmask_b32_e32 v148, v171, v148, vcc
	v_lshlrev_b32_e32 v172, 2, v148
	v_mov_b32_e32 v148, v175
	v_mov_b32_e32 v175, v177
	v_pk_add_f32 v[148:149], v[148:149], v[174:175]
	v_mov_b32_e32 v174, v179
	v_mov_b32_e32 v175, v180
	v_mov_b32_e32 v179, v181
	v_mov_b32_e32 v176, v183
	v_mov_b32_e32 v177, v184
	v_mov_b32_e32 v183, v185
	v_mov_b32_e32 v180, v187
	v_mov_b32_e32 v181, v188
	v_mov_b32_e32 v187, v189
	v_pk_add_f32 v[174:175], v[174:175], v[178:179]
	v_pk_add_f32 v[176:177], v[176:177], v[182:183]
	v_pk_add_f32 v[178:179], v[180:181], v[186:187]
	v_mov_b32_e32 v181, v148
	v_mov_b32_e32 v180, v174
	v_mov_b32_e32 v148, v175
	v_mov_b32_e32 v174, v178
	v_mov_b32_e32 v175, v176
	v_mov_b32_e32 v176, v179
	v_pk_add_f32 v[148:149], v[180:181], v[148:149]
	v_pk_add_f32 v[174:175], v[174:175], v[176:177]
	ds_bpermute_b32 v177, v172, v149
	ds_bpermute_b32 v176, v172, v148
	ds_bpermute_b32 v179, v172, v175
	ds_bpermute_b32 v178, v172, v174
	v_cmp_lt_i32_e32 vcc, v173, v191
	v_add_u32_e32 v182, v152, v150
	s_waitcnt lgkmcnt(2)
	v_pk_add_f32 v[176:177], v[148:149], v[176:177]
	v_cndmask_b32_e32 v173, v171, v173, vcc
	v_lshlrev_b32_e32 v173, 2, v173
	s_waitcnt lgkmcnt(0)
	v_pk_add_f32 v[174:175], v[174:175], v[178:179]
	ds_bpermute_b32 v179, v173, v177
	ds_bpermute_b32 v178, v173, v176
	ds_bpermute_b32 v181, v173, v175
	ds_bpermute_b32 v180, v173, v174
	v_mov_b64_e32 v[148:149], s[20:21]
	v_ashrrev_i32_e32 v183, 31, v182
	s_waitcnt lgkmcnt(2)
	v_pk_add_f32 v[176:177], v[176:177], v[178:179]
	s_waitcnt lgkmcnt(0)
	v_pk_add_f32 v[174:175], v[174:175], v[180:181]
	v_pk_fma_f32 v[176:177], v[176:177], s[18:19], v[148:149] op_sel_hi:[1,0,0]
	v_pk_fma_f32 v[174:175], v[174:175], s[18:19], v[148:149] op_sel_hi:[1,0,0]
	v_mul_f32_e32 v150, 0x4b800000, v177
	v_cmp_gt_f32_e32 vcc, s62, v177
	v_mul_f32_e32 v152, 0x4b800000, v176
	v_mul_f32_e32 v178, 0x4b800000, v175
	v_cndmask_b32_e32 v150, v177, v150, vcc
	v_mul_f32_e32 v179, 0x4b800000, v174
	v_cmp_gt_f32_e64 s[6:7], s62, v176
	v_cmp_gt_f32_e64 s[8:9], s62, v175
	v_cmp_gt_f32_e64 s[10:11], s62, v174
	v_rsq_f32_e32 v150, v150
	v_cndmask_b32_e64 v152, v176, v152, s[6:7]
	v_cndmask_b32_e64 v175, v175, v178, s[8:9]
	v_cndmask_b32_e64 v174, v174, v179, s[10:11]
	v_rsq_f32_e32 v152, v152
	v_rsq_f32_e32 v175, v175
	v_rsq_f32_e32 v177, v174
	v_mul_f32_e32 v174, 0x45800000, v150
	v_cndmask_b32_e32 v174, v150, v174, vcc
	v_mul_f32_e32 v176, 0x45800000, v152
	v_mul_f32_e32 v178, 0x45800000, v175
	v_mul_f32_e32 v179, 0x45800000, v177
	v_pk_mul_f32 v[124:125], v[124:125], v[174:175] op_sel_hi:[1,0]
	v_pk_mul_f32 v[126:127], v[126:127], v[174:175] op_sel_hi:[1,0]
	v_cndmask_b32_e64 v176, v152, v176, s[6:7]
	v_cndmask_b32_e64 v152, v175, v178, s[8:9]
	v_cndmask_b32_e64 v150, v177, v179, s[10:11]
	v_pk_mul_f32 v[120:121], v[120:121], v[174:175] op_sel_hi:[1,0]
	v_pk_mul_f32 v[122:123], v[122:123], v[174:175] op_sel_hi:[1,0]
	v_pk_mul_f32 v[116:117], v[116:117], v[174:175] op_sel_hi:[1,0]
	v_mul_f32_e32 v175, 0xbfb8aa3b, v124
	v_mul_f32_e32 v178, 0xbfb8aa3b, v126
	v_mul_f32_e32 v179, 0xbfb8aa3b, v127
	v_exp_f32_e32 v175, v175
	v_exp_f32_e32 v178, v178
	v_exp_f32_e32 v179, v179
	v_mul_f32_e32 v177, 0xbfb8aa3b, v125
	v_mul_f32_e32 v184, 0xbfb8aa3b, v116
	v_exp_f32_e32 v177, v177
	v_add_f32_e32 v175, 1.0, v175
	v_add_f32_e32 v180, 1.0, v178
	v_add_f32_e32 v181, 1.0, v179
	v_rcp_f32_e32 v178, v175
	v_rcp_f32_e32 v180, v180
	v_rcp_f32_e32 v181, v181
	v_exp_f32_e32 v175, v184
	v_add_f32_e32 v177, 1.0, v177
	v_mul_f32_e32 v185, 0xbfb8aa3b, v117
	v_rcp_f32_e32 v179, v177
	v_pk_mul_f32 v[126:127], v[126:127], v[180:181]
	v_pk_mul_f32 v[118:119], v[118:119], v[174:175] op_sel_hi:[1,0]
	v_exp_f32_e32 v177, v185
	v_pk_mul_f32 v[122:123], v[122:123], v[126:127]
	v_mul_f32_e32 v126, 0xbfb8aa3b, v118
	v_mul_f32_e32 v127, 0xbfb8aa3b, v119
	v_exp_f32_e32 v126, v126
	v_exp_f32_e32 v127, v127
	v_pk_mul_f32 v[124:125], v[124:125], v[178:179]
	v_pk_mul_f32 v[112:113], v[112:113], v[174:175] op_sel_hi:[1,0]
	v_pk_mul_f32 v[120:121], v[120:121], v[124:125]
	v_add_f32_e32 v124, 1.0, v175
; __device__ __forceinline__ unsigned pk2(float lo, float hi) { f32x2_t v = {lo, hi}; bf16x2_t b = __builtin_convertvector(v, bf16x2_t); return __builtin_bit_cast(unsigned, b); }
; __device__ __forceinline__ float sigm(float x) { return frcp(1.f + fexp2(-LOG2E * x)); }
;   __device__ __forceinline__ void operator()(const pg8::f32x4 (&acc)[2][2][4][2], const pg8::Unit& u, int wr, int wc, int fr, int fq) const {
;     ...
;       for (int m = 0; m < 4; ++m) {
;         const float r = rs[m]; float v[8];
; #pragma unroll
;         for (int n = 0; n < 2; ++n)
; #pragma unroll
;           for (int c = 0; c < 4; ++c) { const float g = acc[ai][0][m][n][c] * r, uu = acc[ai][1][m][n][c] * r; v[4 * n + c] = g * sigm(g) * uu; }
;         u32x4 w; w.x = pk2(v[0], v[1]); w.y = pk2(v[2], v[3]); w.z = pk2(v[4], v[5]); w.w = pk2(v[6], v[7]);
;         *(u32x4*)(hbuf + (unsigned)(row0 + ai * 128 + m * 16) * DFF + col0) = w;
	v_add_f32_e32 v125, 1.0, v177
	v_rcp_f32_e32 v124, v124
	v_rcp_f32_e32 v125, v125
	v_add_f32_e32 v126, 1.0, v126
	v_add_f32_e32 v127, 1.0, v127
	v_rcp_f32_e32 v126, v126
	v_rcp_f32_e32 v127, v127
	v_pk_mul_f32 v[116:117], v[116:117], v[124:125]
	v_pk_mul_f32 v[114:115], v[114:115], v[174:175] op_sel_hi:[1,0]
	v_pk_mul_f32 v[112:113], v[112:113], v[116:117]
	v_pk_mul_f32 v[116:117], v[118:119], v[126:127]
	v_cvt_pk_bf16_f32 v118, v112, v113
	v_pk_mul_f32 v[114:115], v[114:115], v[116:117]
	v_cvt_pk_bf16_f32 v116, v120, v121
	v_cvt_pk_bf16_f32 v119, v114, v115
	v_mul_lo_u32 v114, v190, s63
	v_mov_b32_e32 v115, v137
	v_lshl_add_u64 v[120:121], v[114:115], 1, s[38:39]
	v_lshlrev_b64 v[112:113], 1, v[182:183]
	v_pk_mul_f32 v[108:109], v[108:109], v[176:177] op_sel_hi:[1,0]
	v_cvt_pk_bf16_f32 v117, v122, v123
	v_lshl_add_u64 v[120:121], v[120:121], 0, v[112:113]
	v_mul_f32_e32 v115, 0xbfb8aa3b, v108
	v_exp_f32_e32 v115, v115
	global_store_dwordx4 v[120:121], v[116:119], off
	v_pk_mul_f32 v[110:111], v[110:111], v[176:177] op_sel_hi:[1,0]
	v_pk_mul_f32 v[100:101], v[100:101], v[176:177] op_sel_hi:[1,0]
	v_mul_f32_e32 v116, 0xbfb8aa3b, v109
	v_exp_f32_e32 v117, v116
	v_add_f32_e32 v115, 1.0, v115
	v_rcp_f32_e32 v116, v115
	v_pk_mul_f32 v[104:105], v[104:105], v[176:177] op_sel_hi:[1,0]
	v_add_f32_e32 v115, 1.0, v117
	v_mul_f32_e32 v117, 0xbfb8aa3b, v110
	v_exp_f32_e32 v118, v117
	v_mul_f32_e32 v117, 0xbfb8aa3b, v111
	v_exp_f32_e32 v119, v117
	v_rcp_f32_e32 v117, v115
	v_add_f32_e32 v115, 1.0, v118
	v_rcp_f32_e32 v118, v115
	v_add_f32_e32 v115, 1.0, v119
	v_rcp_f32_e32 v119, v115
	v_pk_mul_f32 v[108:109], v[108:109], v[116:117]
	v_pk_mul_f32 v[102:103], v[102:103], v[176:177] op_sel_hi:[1,0]
	v_pk_mul_f32 v[100:101], v[100:101], v[108:109]
	v_pk_mul_f32 v[108:109], v[110:111], v[118:119]
	v_mul_f32_e32 v110, 0xbfb8aa3b, v104
	v_exp_f32_e32 v110, v110
	v_pk_mul_f32 v[102:103], v[102:103], v[108:109]
	v_mul_f32_e32 v108, 0xbfb8aa3b, v105
	v_pk_mul_f32 v[106:107], v[106:107], v[176:177] op_sel_hi:[1,0]
	v_exp_f32_e32 v109, v108
	v_add_f32_e32 v108, 1.0, v110
	v_mul_f32_e32 v110, 0xbfb8aa3b, v106
	v_mul_f32_e32 v111, 0xbfb8aa3b, v107
	v_exp_f32_e32 v110, v110
	v_exp_f32_e32 v111, v111
	v_add_f32_e32 v109, 1.0, v109
	v_rcp_f32_e32 v108, v108
	v_rcp_f32_e32 v109, v109
	v_add_f32_e32 v110, 1.0, v110
	v_add_f32_e32 v111, 1.0, v111
	v_rcp_f32_e32 v110, v110
	v_rcp_f32_e32 v111, v111
	v_pk_mul_f32 v[96:97], v[96:97], v[176:177] op_sel_hi:[1,0]
	v_pk_mul_f32 v[104:105], v[104:105], v[108:109]
	v_pk_mul_f32 v[92:93], v[92:93], v[152:153] op_sel_hi:[1,0]
	v_pk_mul_f32 v[104:105], v[96:97], v[104:105]
	v_pk_mul_f32 v[96:97], v[98:99], v[176:177] op_sel_hi:[1,0]
	v_pk_mul_f32 v[98:99], v[106:107], v[110:111]
	v_pk_mul_f32 v[94:95], v[94:95], v[152:153] op_sel_hi:[1,0]
	v_pk_mul_f32 v[106:107], v[96:97], v[98:99]
	v_cvt_pk_bf16_f32 v96, v100, v101
	v_add_u32_e32 v100, 0xb000, v114
	v_mov_b32_e32 v101, v137
	v_lshl_add_u64 v[100:101], v[100:101], 1, s[38:39]
	v_cvt_pk_bf16_f32 v97, v102, v103
	v_cvt_pk_bf16_f32 v98, v104, v105
	v_cvt_pk_bf16_f32 v99, v106, v107
	v_lshl_add_u64 v[100:101], v[100:101], 0, v[112:113]
	v_mul_f32_e32 v102, 0xbfb8aa3b, v92
	global_store_dwordx4 v[100:101], v[96:99], off
	v_exp_f32_e32 v102, v102
	v_pk_mul_f32 v[84:85], v[84:85], v[152:153] op_sel_hi:[1,0]
	v_mul_f32_e32 v96, 0xbfb8aa3b, v93
	v_exp_f32_e32 v97, v96
	v_mul_f32_e32 v98, 0xbfb8aa3b, v94
	v_mul_f32_e32 v99, 0xbfb8aa3b, v95
	v_exp_f32_e32 v98, v98
	v_exp_f32_e32 v99, v99
	v_add_f32_e32 v96, 1.0, v102
	v_add_f32_e32 v97, 1.0, v97
	v_rcp_f32_e32 v96, v96
	v_rcp_f32_e32 v97, v97
	v_add_f32_e32 v98, 1.0, v98
	v_add_f32_e32 v99, 1.0, v99
	v_rcp_f32_e32 v98, v98
	v_rcp_f32_e32 v99, v99
	v_pk_mul_f32 v[92:93], v[92:93], v[96:97]
	v_pk_mul_f32 v[88:89], v[88:89], v[152:153] op_sel_hi:[1,0]
	v_pk_mul_f32 v[84:85], v[84:85], v[92:93]
	v_pk_mul_f32 v[92:93], v[94:95], v[98:99]
	v_mul_f32_e32 v94, 0xbfb8aa3b, v88
	v_exp_f32_e32 v94, v94
	v_pk_mul_f32 v[86:87], v[86:87], v[152:153] op_sel_hi:[1,0]
	v_pk_mul_f32 v[90:91], v[90:91], v[152:153] op_sel_hi:[1,0]
	v_pk_mul_f32 v[86:87], v[86:87], v[92:93]
	v_mul_f32_e32 v92, 0xbfb8aa3b, v89
	v_exp_f32_e32 v93, v92
	v_add_f32_e32 v92, 1.0, v94
	v_mul_f32_e32 v94, 0xbfb8aa3b, v90
	v_mul_f32_e32 v95, 0xbfb8aa3b, v91
	v_exp_f32_e32 v94, v94
	v_exp_f32_e32 v95, v95
	v_add_f32_e32 v93, 1.0, v93
	v_rcp_f32_e32 v92, v92
	v_rcp_f32_e32 v93, v93
	v_add_f32_e32 v94, 1.0, v94
	v_add_f32_e32 v95, 1.0, v95
	v_rcp_f32_e32 v94, v94
	v_rcp_f32_e32 v95, v95
	v_pk_mul_f32 v[80:81], v[80:81], v[152:153] op_sel_hi:[1,0]
	v_pk_mul_f32 v[88:89], v[88:89], v[92:93]
	v_pk_mul_f32 v[76:77], v[76:77], v[150:151] op_sel_hi:[1,0]
	v_pk_mul_f32 v[88:89], v[80:81], v[88:89]
	v_pk_mul_f32 v[80:81], v[82:83], v[152:153] op_sel_hi:[1,0]
	v_pk_mul_f32 v[82:83], v[90:91], v[94:95]
	v_pk_mul_f32 v[78:79], v[78:79], v[150:151] op_sel_hi:[1,0]
	v_pk_mul_f32 v[90:91], v[80:81], v[82:83]
	v_cvt_pk_bf16_f32 v80, v84, v85
	v_add_u32_e32 v84, 0x16000, v114
	v_mov_b32_e32 v85, v137
	v_lshl_add_u64 v[84:85], v[84:85], 1, s[38:39]
	v_cvt_pk_bf16_f32 v81, v86, v87
	v_cvt_pk_bf16_f32 v82, v88, v89
	v_cvt_pk_bf16_f32 v83, v90, v91
	v_lshl_add_u64 v[84:85], v[84:85], 0, v[112:113]
	v_mul_f32_e32 v86, 0xbfb8aa3b, v76
	global_store_dwordx4 v[84:85], v[80:83], off
	v_exp_f32_e32 v86, v86
	v_pk_mul_f32 v[68:69], v[68:69], v[150:151] op_sel_hi:[1,0]
	v_mul_f32_e32 v80, 0xbfb8aa3b, v77
	v_exp_f32_e32 v81, v80
	v_mul_f32_e32 v82, 0xbfb8aa3b, v78
	v_mul_f32_e32 v83, 0xbfb8aa3b, v79
	v_exp_f32_e32 v82, v82
	v_exp_f32_e32 v83, v83
	v_add_f32_e32 v80, 1.0, v86
	v_add_f32_e32 v81, 1.0, v81
; __device__ __forceinline__ unsigned pk2(float lo, float hi) { f32x2_t v = {lo, hi}; bf16x2_t b = __builtin_convertvector(v, bf16x2_t); return __builtin_bit_cast(unsigned, b); }
; __device__ __forceinline__ float sigm(float x) { return frcp(1.f + fexp2(-LOG2E * x)); }
;   __device__ __forceinline__ void operator()(const pg8::f32x4 (&acc)[2][2][4][2], const pg8::Unit& u, int wr, int wc, int fr, int fq) const {
;     ...
;       for (int m = 0; m < 4; ++m) { const f32x4 a = *(const f32x4*)(ssq + (unsigned)(row0 + ai * 128 + m * 16) * 16 + 4 * fq); rs[m] = (a[0] + a[1]) + (a[2] + a[3]); }
; #pragma unroll
;       for (int m = 0; m < 4; ++m) { float v = rs[m]; v += __shfl_xor(v, 16); v += __shfl_xor(v, 32); rs[m] = rsqrtf(v * (1.f / 1024.f) + EPS); }
; #pragma unroll
;       for (int m = 0; m < 4; ++m) {
;         const float r = rs[m]; float v[8];
; #pragma unroll
;         for (int n = 0; n < 2; ++n)
; #pragma unroll
;           for (int c = 0; c < 4; ++c) { const float g = acc[ai][0][m][n][c] * r, uu = acc[ai][1][m][n][c] * r; v[4 * n + c] = g * sigm(g) * uu; }
;         u32x4 w; w.x = pk2(v[0], v[1]); w.y = pk2(v[2], v[3]); w.z = pk2(v[4], v[5]); w.w = pk2(v[6], v[7]);
	v_rcp_f32_e32 v80, v80
	v_rcp_f32_e32 v81, v81
	v_add_f32_e32 v82, 1.0, v82
	v_add_f32_e32 v83, 1.0, v83
	v_rcp_f32_e32 v82, v82
	v_rcp_f32_e32 v83, v83
	v_pk_mul_f32 v[76:77], v[76:77], v[80:81]
	v_pk_mul_f32 v[72:73], v[72:73], v[150:151] op_sel_hi:[1,0]
	v_pk_mul_f32 v[68:69], v[68:69], v[76:77]
	v_pk_mul_f32 v[76:77], v[78:79], v[82:83]
	v_mul_f32_e32 v78, 0xbfb8aa3b, v72
	v_exp_f32_e32 v78, v78
	v_pk_mul_f32 v[70:71], v[70:71], v[150:151] op_sel_hi:[1,0]
	v_pk_mul_f32 v[74:75], v[74:75], v[150:151] op_sel_hi:[1,0]
	v_pk_mul_f32 v[70:71], v[70:71], v[76:77]
	v_mul_f32_e32 v76, 0xbfb8aa3b, v73
	v_exp_f32_e32 v77, v76
	v_add_f32_e32 v76, 1.0, v78
	v_mul_f32_e32 v78, 0xbfb8aa3b, v74
	v_mul_f32_e32 v79, 0xbfb8aa3b, v75
	v_exp_f32_e32 v78, v78
	v_exp_f32_e32 v79, v79
	v_add_f32_e32 v77, 1.0, v77
	v_rcp_f32_e32 v76, v76
	v_rcp_f32_e32 v77, v77
	v_add_f32_e32 v78, 1.0, v78
	v_add_f32_e32 v79, 1.0, v79
	v_rcp_f32_e32 v78, v78
	v_rcp_f32_e32 v79, v79
	v_pk_mul_f32 v[64:65], v[64:65], v[150:151] op_sel_hi:[1,0]
	v_pk_mul_f32 v[72:73], v[72:73], v[76:77]
	s_nop 0
	v_pk_mul_f32 v[72:73], v[64:65], v[72:73]
	v_pk_mul_f32 v[64:65], v[66:67], v[150:151] op_sel_hi:[1,0]
	v_pk_mul_f32 v[66:67], v[74:75], v[78:79]
	s_nop 0
	v_pk_mul_f32 v[74:75], v[64:65], v[66:67]
	v_cvt_pk_bf16_f32 v64, v68, v69
	v_add_u32_e32 v68, 0x21000, v114
	v_mov_b32_e32 v69, v137
	v_lshl_add_u64 v[68:69], v[68:69], 1, s[38:39]
	v_cvt_pk_bf16_f32 v65, v70, v71
	v_cvt_pk_bf16_f32 v66, v72, v73
	v_cvt_pk_bf16_f32 v67, v74, v75
	v_lshl_add_u64 v[68:69], v[68:69], 0, v[112:113]
	global_store_dwordx4 v[68:69], v[64:67], off
	v_add_u32_e32 v136, 0x58000, v114
	v_mov_b64_e32 v[72:73], v[208:209]
	v_mov_b64_e32 v[74:75], v[210:211]
	v_mov_b64_e32 v[76:77], v[212:213]
	v_mov_b64_e32 v[78:79], v[214:215]
	v_mov_b64_e32 v[64:65], v[200:201]
	v_mov_b64_e32 v[66:67], v[202:203]
	v_mov_b64_e32 v[68:69], v[204:205]
	v_mov_b64_e32 v[70:71], v[206:207]
	v_mov_b32_e32 v80, v65
	v_mov_b32_e32 v81, v66
	v_mov_b32_e32 v65, v67
	v_mov_b32_e32 v66, v69
	v_mov_b32_e32 v67, v70
	v_mov_b32_e32 v69, v71
	v_pk_add_f32 v[64:65], v[80:81], v[64:65]
	v_pk_add_f32 v[66:67], v[66:67], v[68:69]
	v_mov_b32_e32 v69, v64
	v_mov_b32_e32 v68, v66
	v_mov_b32_e32 v64, v67
	v_pk_add_f32 v[64:65], v[68:69], v[64:65]
	ds_bpermute_b32 v67, v172, v65
	ds_bpermute_b32 v66, v172, v64
	v_mov_b32_e32 v68, v73
	v_mov_b32_e32 v69, v74
	v_mov_b32_e32 v73, v75
	v_mov_b32_e32 v70, v77
	s_waitcnt lgkmcnt(0)
	v_pk_add_f32 v[64:65], v[64:65], v[66:67]
	ds_bpermute_b32 v67, v173, v65
	ds_bpermute_b32 v66, v173, v64
	v_mov_b32_e32 v71, v78
	v_mov_b32_e32 v77, v79
	v_pk_add_f32 v[68:69], v[68:69], v[72:73]
	v_pk_add_f32 v[70:71], v[70:71], v[76:77]
	s_waitcnt lgkmcnt(0)
	v_pk_add_f32 v[64:65], v[64:65], v[66:67]
	v_mov_b32_e32 v67, v68
	v_pk_fma_f32 v[64:65], v[64:65], s[18:19], v[148:149] op_sel_hi:[1,0,0]
	v_mov_b32_e32 v68, v71
	v_mul_f32_e32 v66, 0x4b800000, v65
	v_cmp_gt_f32_e32 vcc, s62, v65
	v_cmp_gt_f32_e64 s[6:7], s62, v64
	s_nop 0
	v_cndmask_b32_e32 v65, v65, v66, vcc
	v_mov_b32_e32 v66, v70
	v_pk_add_f32 v[66:67], v[66:67], v[68:69]
	ds_bpermute_b32 v69, v172, v67
	ds_bpermute_b32 v68, v172, v66
	v_rsq_f32_e32 v72, v65
	v_mul_f32_e32 v65, 0x4b800000, v64
	v_cndmask_b32_e64 v64, v64, v65, s[6:7]
	v_rsq_f32_e32 v70, v64
	s_waitcnt lgkmcnt(0)
	v_pk_add_f32 v[64:65], v[66:67], v[68:69]
	ds_bpermute_b32 v67, v173, v65
	ds_bpermute_b32 v66, v173, v64
	v_mul_f32_e32 v68, 0x45800000, v72
	v_cndmask_b32_e32 v68, v72, v68, vcc
	v_mul_f32_e32 v69, 0x45800000, v70
	v_pk_mul_f32 v[62:63], v[62:63], v[68:69] op_sel_hi:[1,0]
	s_waitcnt lgkmcnt(0)
	v_pk_add_f32 v[64:65], v[64:65], v[66:67]
	v_pk_mul_f32 v[56:57], v[56:57], v[68:69] op_sel_hi:[1,0]
	v_pk_fma_f32 v[64:65], v[64:65], s[18:19], v[148:149] op_sel_hi:[1,0,0]
	v_pk_mul_f32 v[54:55], v[54:55], v[68:69] op_sel_hi:[1,0]
	v_mul_f32_e32 v66, 0x4b800000, v65
	v_cmp_gt_f32_e32 vcc, s62, v65
	v_cmp_gt_f32_e64 s[8:9], s62, v64
	v_pk_mul_f32 v[58:59], v[58:59], v[68:69] op_sel_hi:[1,0]
	v_cndmask_b32_e32 v65, v65, v66, vcc
	v_mul_f32_e32 v66, 0x4b800000, v64
	v_rsq_f32_e32 v65, v65
	v_cndmask_b32_e64 v64, v64, v66, s[8:9]
	v_rsq_f32_e32 v67, v64
	v_cndmask_b32_e64 v66, v70, v69, s[6:7]
	v_mul_f32_e32 v64, 0x45800000, v65
	v_pk_mul_f32 v[70:71], v[60:61], v[68:69] op_sel_hi:[1,0]
	v_cndmask_b32_e32 v64, v65, v64, vcc
	v_mul_f32_e32 v65, 0x45800000, v67
	v_mul_f32_e32 v60, 0xbfb8aa3b, v70
	v_exp_f32_e32 v61, v60
	v_cndmask_b32_e64 v60, v67, v65, s[8:9]
	v_mul_f32_e32 v65, 0xbfb8aa3b, v71
	v_exp_f32_e32 v65, v65
	v_add_f32_e32 v61, 1.0, v61
	v_rcp_f32_e32 v72, v61
	v_mul_f32_e32 v67, 0xbfb8aa3b, v63
	v_add_f32_e32 v61, 1.0, v65
	v_mul_f32_e32 v65, 0xbfb8aa3b, v62
	v_exp_f32_e32 v65, v65
	v_exp_f32_e32 v67, v67
	v_rcp_f32_e32 v73, v61
	v_pk_mul_f32 v[52:53], v[52:53], v[68:69] op_sel_hi:[1,0]
	v_add_f32_e32 v61, 1.0, v65
	v_rcp_f32_e32 v74, v61
	v_add_f32_e32 v61, 1.0, v67
	v_rcp_f32_e32 v75, v61
	v_mul_f32_e32 v61, 0xbfb8aa3b, v56
	v_exp_f32_e32 v61, v61
	v_pk_mul_f32 v[70:71], v[70:71], v[72:73]
	v_pk_mul_f32 v[62:63], v[62:63], v[74:75]
	v_pk_mul_f32 v[52:53], v[52:53], v[70:71]
	v_pk_mul_f32 v[54:55], v[54:55], v[62:63]
	v_mul_f32_e32 v62, 0xbfb8aa3b, v57
	v_exp_f32_e32 v63, v62
	v_add_f32_e32 v61, 1.0, v61
	v_rcp_f32_e32 v62, v61
	v_pk_mul_f32 v[48:49], v[48:49], v[68:69] op_sel_hi:[1,0]
	v_add_f32_e32 v61, 1.0, v63
	v_mul_f32_e32 v63, 0xbfb8aa3b, v58
	v_exp_f32_e32 v65, v63
	v_mul_f32_e32 v63, 0xbfb8aa3b, v59
	v_exp_f32_e32 v67, v63
	v_rcp_f32_e32 v63, v61
	v_add_f32_e32 v61, 1.0, v65
	v_rcp_f32_e32 v70, v61
	v_add_f32_e32 v61, 1.0, v67
	v_rcp_f32_e32 v71, v61
	v_pk_mul_f32 v[56:57], v[56:57], v[62:63]
; __device__ __forceinline__ unsigned pk2(float lo, float hi) { f32x2_t v = {lo, hi}; bf16x2_t b = __builtin_convertvector(v, bf16x2_t); return __builtin_bit_cast(unsigned, b); }
; __device__ __forceinline__ float sigm(float x) { return frcp(1.f + fexp2(-LOG2E * x)); }
;   __device__ __forceinline__ void operator()(const pg8::f32x4 (&acc)[2][2][4][2], const pg8::Unit& u, int wr, int wc, int fr, int fq) const {
;     ...
;       for (int m = 0; m < 4; ++m) {
;         const float r = rs[m]; float v[8];
; #pragma unroll
;         for (int n = 0; n < 2; ++n)
; #pragma unroll
;           for (int c = 0; c < 4; ++c) { const float g = acc[ai][0][m][n][c] * r, uu = acc[ai][1][m][n][c] * r; v[4 * n + c] = g * sigm(g) * uu; }
;         u32x4 w; w.x = pk2(v[0], v[1]); w.y = pk2(v[2], v[3]); w.z = pk2(v[4], v[5]); w.w = pk2(v[6], v[7]);
;         *(u32x4*)(hbuf + (unsigned)(row0 + ai * 128 + m * 16) * DFF + col0) = w;
;       }
	v_pk_mul_f32 v[44:45], v[44:45], v[66:67] op_sel_hi:[1,0]
	v_pk_mul_f32 v[56:57], v[48:49], v[56:57]
	v_pk_mul_f32 v[48:49], v[50:51], v[68:69] op_sel_hi:[1,0]
	v_pk_mul_f32 v[50:51], v[58:59], v[70:71]
	v_pk_mul_f32 v[46:47], v[46:47], v[66:67] op_sel_hi:[1,0]
	v_pk_mul_f32 v[58:59], v[48:49], v[50:51]
	v_cvt_pk_bf16_f32 v48, v52, v53
	v_lshl_add_u64 v[52:53], v[136:137], 1, s[38:39]
	v_cvt_pk_bf16_f32 v49, v54, v55
	v_cvt_pk_bf16_f32 v50, v56, v57
	v_cvt_pk_bf16_f32 v51, v58, v59
	v_lshl_add_u64 v[52:53], v[52:53], 0, v[112:113]
	v_mul_f32_e32 v54, 0xbfb8aa3b, v44
	global_store_dwordx4 v[52:53], v[48:51], off
	v_exp_f32_e32 v54, v54
	v_pk_mul_f32 v[36:37], v[36:37], v[66:67] op_sel_hi:[1,0]
	v_mul_f32_e32 v48, 0xbfb8aa3b, v45
	v_exp_f32_e32 v49, v48
	v_mul_f32_e32 v50, 0xbfb8aa3b, v46
	v_mul_f32_e32 v51, 0xbfb8aa3b, v47
	v_exp_f32_e32 v50, v50
	v_exp_f32_e32 v51, v51
	v_add_f32_e32 v48, 1.0, v54
	v_add_f32_e32 v49, 1.0, v49
	v_rcp_f32_e32 v48, v48
	v_rcp_f32_e32 v49, v49
	v_add_f32_e32 v50, 1.0, v50
	v_add_f32_e32 v51, 1.0, v51
	v_rcp_f32_e32 v50, v50
	v_rcp_f32_e32 v51, v51
	v_pk_mul_f32 v[44:45], v[44:45], v[48:49]
	v_pk_mul_f32 v[40:41], v[40:41], v[66:67] op_sel_hi:[1,0]
	v_pk_mul_f32 v[36:37], v[36:37], v[44:45]
	v_pk_mul_f32 v[44:45], v[46:47], v[50:51]
	v_mul_f32_e32 v46, 0xbfb8aa3b, v40
	v_exp_f32_e32 v46, v46
	v_pk_mul_f32 v[38:39], v[38:39], v[66:67] op_sel_hi:[1,0]
	v_pk_mul_f32 v[42:43], v[42:43], v[66:67] op_sel_hi:[1,0]
	v_pk_mul_f32 v[38:39], v[38:39], v[44:45]
	v_mul_f32_e32 v44, 0xbfb8aa3b, v41
	v_exp_f32_e32 v45, v44
	v_add_f32_e32 v44, 1.0, v46
	v_mul_f32_e32 v46, 0xbfb8aa3b, v42
	v_mul_f32_e32 v47, 0xbfb8aa3b, v43
	v_exp_f32_e32 v46, v46
	v_exp_f32_e32 v47, v47
	v_add_f32_e32 v45, 1.0, v45
	v_rcp_f32_e32 v44, v44
	v_rcp_f32_e32 v45, v45
	v_add_f32_e32 v46, 1.0, v46
	v_add_f32_e32 v47, 1.0, v47
	v_rcp_f32_e32 v46, v46
	v_rcp_f32_e32 v47, v47
	v_pk_mul_f32 v[32:33], v[32:33], v[66:67] op_sel_hi:[1,0]
	v_pk_mul_f32 v[40:41], v[40:41], v[44:45]
	v_add_u32_e32 v136, 0x63000, v114
	v_pk_mul_f32 v[40:41], v[32:33], v[40:41]
	v_pk_mul_f32 v[32:33], v[34:35], v[66:67] op_sel_hi:[1,0]
	v_pk_mul_f32 v[34:35], v[42:43], v[46:47]
	v_pk_mul_f32 v[28:29], v[28:29], v[64:65] op_sel_hi:[1,0]
	v_pk_mul_f32 v[42:43], v[32:33], v[34:35]
	v_cvt_pk_bf16_f32 v32, v36, v37
	v_lshl_add_u64 v[36:37], v[136:137], 1, s[38:39]
	v_cvt_pk_bf16_f32 v33, v38, v39
	v_cvt_pk_bf16_f32 v34, v40, v41
	v_cvt_pk_bf16_f32 v35, v42, v43
	v_lshl_add_u64 v[36:37], v[36:37], 0, v[112:113]
	v_mul_f32_e32 v38, 0xbfb8aa3b, v28
	global_store_dwordx4 v[36:37], v[32:35], off
	v_pk_mul_f32 v[30:31], v[30:31], v[64:65] op_sel_hi:[1,0]
	v_exp_f32_e32 v38, v38
	v_mul_f32_e32 v32, 0xbfb8aa3b, v29
	v_exp_f32_e32 v33, v32
	v_mul_f32_e32 v34, 0xbfb8aa3b, v30
	v_mul_f32_e32 v35, 0xbfb8aa3b, v31
	v_exp_f32_e32 v34, v34
	v_exp_f32_e32 v35, v35
	v_add_f32_e32 v32, 1.0, v38
	v_add_f32_e32 v33, 1.0, v33
	v_rcp_f32_e32 v32, v32
	v_rcp_f32_e32 v33, v33
	v_add_f32_e32 v34, 1.0, v34
	v_add_f32_e32 v35, 1.0, v35
	v_rcp_f32_e32 v34, v34
	v_rcp_f32_e32 v35, v35
	v_pk_mul_f32 v[20:21], v[20:21], v[64:65] op_sel_hi:[1,0]
	v_pk_mul_f32 v[28:29], v[28:29], v[32:33]
	v_pk_mul_f32 v[24:25], v[24:25], v[64:65] op_sel_hi:[1,0]
	v_pk_mul_f32 v[20:21], v[20:21], v[28:29]
	v_pk_mul_f32 v[28:29], v[30:31], v[34:35]
	v_mul_f32_e32 v30, 0xbfb8aa3b, v24
	v_exp_f32_e32 v30, v30
	v_pk_mul_f32 v[22:23], v[22:23], v[64:65] op_sel_hi:[1,0]
	v_pk_mul_f32 v[26:27], v[26:27], v[64:65] op_sel_hi:[1,0]
	v_pk_mul_f32 v[22:23], v[22:23], v[28:29]
	v_mul_f32_e32 v28, 0xbfb8aa3b, v25
	v_exp_f32_e32 v29, v28
	v_add_f32_e32 v28, 1.0, v30
	v_mul_f32_e32 v30, 0xbfb8aa3b, v26
	v_mul_f32_e32 v31, 0xbfb8aa3b, v27
	v_exp_f32_e32 v30, v30
	v_exp_f32_e32 v31, v31
	v_add_f32_e32 v29, 1.0, v29
	v_rcp_f32_e32 v28, v28
	v_rcp_f32_e32 v29, v29
	v_add_f32_e32 v30, 1.0, v30
	v_add_f32_e32 v31, 1.0, v31
	v_rcp_f32_e32 v30, v30
	v_rcp_f32_e32 v31, v31
	v_pk_mul_f32 v[16:17], v[16:17], v[64:65] op_sel_hi:[1,0]
	v_pk_mul_f32 v[24:25], v[24:25], v[28:29]
	v_add_u32_e32 v136, 0x6e000, v114
	v_pk_mul_f32 v[24:25], v[16:17], v[24:25]
	v_pk_mul_f32 v[16:17], v[18:19], v[64:65] op_sel_hi:[1,0]
	v_pk_mul_f32 v[18:19], v[26:27], v[30:31]
	v_pk_mul_f32 v[12:13], v[12:13], v[60:61] op_sel_hi:[1,0]
	v_pk_mul_f32 v[26:27], v[16:17], v[18:19]
	v_cvt_pk_bf16_f32 v16, v20, v21
	v_lshl_add_u64 v[20:21], v[136:137], 1, s[38:39]
	v_cvt_pk_bf16_f32 v17, v22, v23
	v_cvt_pk_bf16_f32 v18, v24, v25
	v_cvt_pk_bf16_f32 v19, v26, v27
	v_lshl_add_u64 v[20:21], v[20:21], 0, v[112:113]
	v_mul_f32_e32 v22, 0xbfb8aa3b, v12
	global_store_dwordx4 v[20:21], v[16:19], off
	v_pk_mul_f32 v[14:15], v[14:15], v[60:61] op_sel_hi:[1,0]
	v_exp_f32_e32 v22, v22
	v_mul_f32_e32 v16, 0xbfb8aa3b, v13
	v_exp_f32_e32 v17, v16
	v_mul_f32_e32 v18, 0xbfb8aa3b, v14
	v_mul_f32_e32 v19, 0xbfb8aa3b, v15
	v_exp_f32_e32 v18, v18
	v_exp_f32_e32 v19, v19
	v_add_f32_e32 v16, 1.0, v22
	v_add_f32_e32 v17, 1.0, v17
	v_rcp_f32_e32 v16, v16
	v_rcp_f32_e32 v17, v17
	v_add_f32_e32 v18, 1.0, v18
	v_add_f32_e32 v19, 1.0, v19
	v_rcp_f32_e32 v18, v18
	v_rcp_f32_e32 v19, v19
	v_pk_mul_f32 v[4:5], v[4:5], v[60:61] op_sel_hi:[1,0]
	v_pk_mul_f32 v[12:13], v[12:13], v[16:17]
	v_pk_mul_f32 v[8:9], v[8:9], v[60:61] op_sel_hi:[1,0]
	v_pk_mul_f32 v[4:5], v[4:5], v[12:13]
	v_pk_mul_f32 v[12:13], v[14:15], v[18:19]
	v_mul_f32_e32 v14, 0xbfb8aa3b, v8
	v_exp_f32_e32 v14, v14
	v_pk_mul_f32 v[6:7], v[6:7], v[60:61] op_sel_hi:[1,0]
	v_pk_mul_f32 v[10:11], v[10:11], v[60:61] op_sel_hi:[1,0]
	v_pk_mul_f32 v[6:7], v[6:7], v[12:13]
	v_mul_f32_e32 v12, 0xbfb8aa3b, v9
	v_exp_f32_e32 v13, v12
	v_add_f32_e32 v12, 1.0, v14
	v_mul_f32_e32 v14, 0xbfb8aa3b, v10
	v_mul_f32_e32 v15, 0xbfb8aa3b, v11
	v_exp_f32_e32 v14, v14
	v_exp_f32_e32 v15, v15
	v_add_f32_e32 v13, 1.0, v13
	v_rcp_f32_e32 v12, v12
	v_rcp_f32_e32 v13, v13
	v_add_f32_e32 v14, 1.0, v14
	v_add_f32_e32 v15, 1.0, v15
	v_rcp_f32_e32 v14, v14
	v_rcp_f32_e32 v15, v15
	v_pk_mul_f32 v[0:1], v[0:1], v[60:61] op_sel_hi:[1,0]
	v_pk_mul_f32 v[8:9], v[8:9], v[12:13]
	v_add_u32_e32 v136, 0x79000, v114
	v_pk_mul_f32 v[8:9], v[0:1], v[8:9]
	v_pk_mul_f32 v[0:1], v[2:3], v[60:61] op_sel_hi:[1,0]
	v_pk_mul_f32 v[2:3], v[10:11], v[14:15]
	s_andn2_b64 vcc, exec, s[4:5]
	v_pk_mul_f32 v[10:11], v[0:1], v[2:3]
	v_cvt_pk_bf16_f32 v0, v4, v5
	v_lshl_add_u64 v[4:5], v[136:137], 1, s[38:39]
	v_cvt_pk_bf16_f32 v1, v6, v7
	v_cvt_pk_bf16_f32 v2, v8, v9
	v_cvt_pk_bf16_f32 v3, v10, v11
	v_lshl_add_u64 v[4:5], v[4:5], 0, v[112:113]
	global_store_dwordx4 v[4:5], v[0:3], off
	s_mov_b64 s[4:5], -1
	s_cbranch_vccnz .LBB0_1603
	s_andn2_b64 vcc, exec, s[12:13]
	s_cbranch_vccnz .LBB0_1602
	s_barrier
	s_branch .LBB0_1602
